# interleaved epilogue halves start after the first 8 MFMAs of their block (bare-MFMA segment head)
# speedup vs baseline: 1.0144x; 1.0056x over previous
; __device__ __forceinline__ unsigned cvt_pk_bf16(float lo, float hi) { unsigned r; asm volatile("v_cvt_pk_bf16_f32 %0, %1, %2" : "=v"(r) : "v"(lo), "v"(hi)); return r; }
; __device__ __forceinline__ float siluf_(float x) { return x * sigmoidf_(x); }
; #define PG8_STAGE(bufoff, gbase, voff) do { _Pragma("unroll") for (int _i = 0; _i < 2; ++_i) \
;         __builtin_amdgcn_global_load_lds((const unsigned*)((const char*)(gbase) + (voff)[_i]), (LAS unsigned*)(lds + (bufoff) + ldsw + _i * 8192), 16, 0, 0); } while (0)
; #define PG8_LDA(dst, b, h) do { _Pragma("unroll") for (int m = 0; m < 4; ++m) _Pragma("unroll") for (int k = 0; k < 2; ++k) dst[m][k] = *(const LAS bf16x8*)(lds + PG8_SA(b, h) + aoff + m * 2048 + k * 1024); } while (0)
;     __device__ __forceinline__ void operator()(const f32x4 (&acc)[2][2][4][2], const Unit& u, int wr, int wc, int fr, int fq) const {
;         const int row0 = u.pm * BM + wr * 64 + fr, col0 = u.pn * HALF + wc * 32 + 8 * fq;
;         float rsv[2][4]; load_rstd(rsv, ssq, row0);
; #pragma unroll
;         for (int ai = 0; ai < 2; ++ai)
; #pragma unroll
;             for (int m = 0; m < 4; ++m) { const int row = row0 + ai * HALF + m * 16; bf16_t* rowp = O + (size_t)row * ldc + col0; const float rs = rsv[ai][m];
;                 f32x4 v0, v1;
; #pragma unroll
;                 for (int j = 0; j < 4; ++j) { v0[j] = siluf_(acc[ai][0][m][0][j] * rs) * (acc[ai][1][m][0][j] * rs); v1[j] = siluf_(acc[ai][0][m][1][j] * rs) * (acc[ai][1][m][1][j] * rs); }
;                 u32x4 w; w.x = cvt_pk_bf16(v0[0], v0[1]); w.y = cvt_pk_bf16(v0[2], v0[3]); w.z = cvt_pk_bf16(v1[0], v1[1]); w.w = cvt_pk_bf16(v1[2], v1[3]);
;                 *(u32x4*)rowp = w; }
; template <class Epi, bool ALIGN_EPI>
; __device__ __forceinline__ void gemm_phase(LAS unsigned char* lds, const Gemm g, const StaticOrder& S, const Epi& E, const int tid) {
;     ...
;             PG8_LDB(B0, 0, 0); PG8_LDB(B1, 0, 1); PG8_SCHED; PG8_LDA(At, 0, 0); PG8_STAGE(PG8_SA(1, 1), a1 + hA, voffA);
;             PG8_WAIT_V(8); PG8_WAIT_L(0); PG8_BAR; PG8_MMA(0, 0, At, B0); PG8_MMA(0, 1, At, B1); PG8_BAR; PG8_SCHED;
;             PG8_LDA(At, 0, 1); PG8_STAGE(PG8_SB(0, 0), b2, voffB); PG8_STAGE(PG8_SB(0, 1), b2 + hB, voffB); PG8_STAGE(PG8_SA(0, 0), a2, voffA);
;             PG8_WAIT_V(8); PG8_WAIT_L(0); PG8_BAR; PG8_MMA(1, 0, At, B0); PG8_MMA(1, 1, At, B1); PG8_BAR; PG8_SCHED;
.Lgu_first_epi:
	s_add_i32 s11, s10, 2
	s_cmp_eq_u32 s58, s10
	v_lshl_add_u64 v[146:147], v[142:143], 0, s[92:93]
	s_cselect_b64 vcc, -1, 0
	v_add_u32_e32 v150, s33, v151
	s_add_i32 s10, 0, 0x14000
	v_cndmask_b32_e32 v167, v147, v139, vcc
	v_cndmask_b32_e32 v166, v146, v138, vcc
	ds_read_b128 v[146:149], v150
	ds_read_b128 v[154:157], v150 offset:1024
	ds_read_b128 v[158:161], v150 offset:2048
	ds_read_b128 v[162:165], v150 offset:3072
	v_add_u32_e32 v150, s10, v151
	ds_read_b128 v[176:179], v150
	ds_read_b128 v[180:183], v150 offset:1024
	ds_read_b128 v[184:187], v150 offset:2048
	ds_read_b128 v[188:191], v150 offset:3072
	v_cndmask_b32_e32 v221, v145, v141, vcc
	v_cndmask_b32_e32 v220, v144, v140, vcc
	v_lshl_add_u64 v[226:227], v[142:143], 0, v[134:135]
	s_add_i32 m0, s51, 0xc000
	ds_read_b128 v[192:195], v153
	ds_read_b128 v[196:199], v153 offset:1024
	ds_read_b128 v[200:203], v153 offset:2048
	ds_read_b128 v[204:207], v153 offset:3072
	ds_read_b128 v[208:211], v153 offset:4096
	ds_read_b128 v[212:215], v153 offset:5120
	ds_read_b128 v[216:219], v153 offset:6144
	ds_read_b128 v[240:243], v153 offset:7168
	global_load_lds_dwordx4 v[226:227], off
	v_lshl_add_u64 v[226:227], v[142:143], 0, v[136:137]
	s_add_i32 m0, s51, 0xe000
	s_nop 0
	global_load_lds_dwordx4 v[226:227], off
	s_waitcnt vmcnt(12)
	s_waitcnt lgkmcnt(0)
	s_barrier
	s_setprio 1
	s_waitcnt lgkmcnt(0)
	v_mfma_f32_16x16x32_bf16 v[120:123], v[146:149], v[192:195], 0
	v_mfma_f32_16x16x32_bf16 v[112:115], v[158:161], v[192:195], 0
	v_mfma_f32_16x16x32_bf16 v[104:107], v[146:149], v[200:203], 0
	v_mfma_f32_16x16x32_bf16 v[96:99], v[158:161], v[200:203], 0
	v_mfma_f32_16x16x32_bf16 v[88:91], v[146:149], v[208:211], 0
	v_mfma_f32_16x16x32_bf16 v[80:83], v[158:161], v[208:211], 0
	v_mfma_f32_16x16x32_bf16 v[72:75], v[146:149], v[216:219], 0
	v_mfma_f32_16x16x32_bf16 v[64:67], v[158:161], v[216:219], 0
	v_mfma_f32_16x16x32_bf16 v[120:123], v[154:157], v[196:199], v[120:123]
	s_lshl_b32 s98, s28, 5
	s_mov_b32 s99, 0
	s_mov_b32 s100, 0xbfb8aa3b
	s_mov_b32 s101, 0xbfb8aa3b
	v_mul_f32_e32 v56, v238, v56
	v_mul_f32_e32 v57, v238, v57
	v_mul_f32_e32 v58, v238, v58
	v_mul_f32_e32 v59, v238, v59
	v_mul_f32_e32 v60, v238, v60
	v_mul_f32_e32 v61, v238, v61
	v_mul_f32_e32 v62, v238, v62
	v_mul_f32_e32 v63, v238, v63
	v_mul_f32_e32 v224, s100, v56
	v_mfma_f32_16x16x32_bf16 v[112:115], v[162:165], v[196:199], v[112:115]
	v_mul_f32_e32 v225, s101, v57
	v_mul_f32_e32 v228, s100, v58
	v_mul_f32_e32 v229, s101, v59
	v_exp_f32_e32 v224, v224
	v_exp_f32_e32 v225, v225
	v_exp_f32_e32 v228, v228
	v_exp_f32_e32 v229, v229
	v_add_f32_e32 v224, 1.0, v224
	v_add_f32_e32 v225, 1.0, v225
	v_add_f32_e32 v228, 1.0, v228
	v_add_f32_e32 v229, 1.0, v229
	v_rcp_f32_e32 v224, v224
	v_rcp_f32_e32 v225, v225
	v_mfma_f32_16x16x32_bf16 v[104:107], v[154:157], v[204:207], v[104:107]
	v_rcp_f32_e32 v228, v228
	v_rcp_f32_e32 v229, v229
	v_nop
	v_mul_f32_e32 v56, v224, v56
	v_mul_f32_e32 v57, v225, v57
	v_mul_f32_e32 v58, v228, v58
	v_mul_f32_e32 v59, v229, v59
	v_mul_f32_e32 v56, v60, v56
	v_mul_f32_e32 v57, v61, v57
	v_mul_f32_e32 v58, v62, v58
	v_mul_f32_e32 v59, v63, v59
	v_mul_f32_e32 v48, v238, v48
	v_mul_f32_e32 v49, v238, v49
	v_mfma_f32_16x16x32_bf16 v[96:99], v[162:165], v[204:207], v[96:99]
	v_mul_f32_e32 v50, v238, v50
	v_mul_f32_e32 v51, v238, v51
	v_mul_f32_e32 v52, v238, v52
	v_mul_f32_e32 v53, v238, v53
	v_mul_f32_e32 v54, v238, v54
	v_mul_f32_e32 v55, v238, v55
	v_mul_f32_e32 v224, s100, v48
	v_mul_f32_e32 v225, s101, v49
	v_mul_f32_e32 v228, s100, v50
	v_mul_f32_e32 v229, s101, v51
	v_exp_f32_e32 v224, v224
	v_exp_f32_e32 v225, v225
	v_exp_f32_e32 v228, v228
	v_mfma_f32_16x16x32_bf16 v[88:91], v[154:157], v[212:215], v[88:91]
	v_exp_f32_e32 v229, v229
	v_add_f32_e32 v224, 1.0, v224
	v_add_f32_e32 v225, 1.0, v225
	v_add_f32_e32 v228, 1.0, v228
	v_add_f32_e32 v229, 1.0, v229
	v_rcp_f32_e32 v224, v224
	v_rcp_f32_e32 v225, v225
	v_rcp_f32_e32 v228, v228
	v_rcp_f32_e32 v229, v229
	v_nop
	v_mul_f32_e32 v48, v224, v48
	v_mul_f32_e32 v49, v225, v49
	v_mul_f32_e32 v50, v228, v50
	v_mfma_f32_16x16x32_bf16 v[80:83], v[162:165], v[212:215], v[80:83]
	v_mul_f32_e32 v51, v229, v51
	v_mul_f32_e32 v48, v52, v48
	v_mul_f32_e32 v49, v53, v49
	v_mul_f32_e32 v50, v54, v50
	v_mul_f32_e32 v51, v55, v51
	v_cvt_pk_bf16_f32 v56, v56, v57
	v_cvt_pk_bf16_f32 v57, v58, v59
	v_cvt_pk_bf16_f32 v58, v48, v49
	v_cvt_pk_bf16_f32 v59, v50, v51
	global_store_dwordx4 v[232:233], v[56:59], off
	v_lshl_add_u64 v[232:233], v[232:233], 0, s[98:99]
	v_mul_f32_e32 v40, v239, v40
	v_mul_f32_e32 v41, v239, v41
	v_mfma_f32_16x16x32_bf16 v[72:75], v[154:157], v[240:243], v[72:75]
	v_mul_f32_e32 v42, v239, v42
	v_mul_f32_e32 v43, v239, v43
	v_mul_f32_e32 v44, v239, v44
	v_mul_f32_e32 v45, v239, v45
	v_mul_f32_e32 v46, v239, v46
	v_mul_f32_e32 v47, v239, v47
	v_mul_f32_e32 v224, s100, v40
	v_mul_f32_e32 v225, s101, v41
	v_mul_f32_e32 v228, s100, v42
	v_mul_f32_e32 v229, s101, v43
	v_exp_f32_e32 v224, v224
	v_exp_f32_e32 v225, v225
	v_exp_f32_e32 v228, v228
	v_mfma_f32_16x16x32_bf16 v[64:67], v[162:165], v[240:243], v[64:67]
	v_exp_f32_e32 v229, v229
	v_add_f32_e32 v224, 1.0, v224
	v_add_f32_e32 v225, 1.0, v225
	v_add_f32_e32 v228, 1.0, v228
	v_add_f32_e32 v229, 1.0, v229
	v_rcp_f32_e32 v224, v224
	v_rcp_f32_e32 v225, v225
	v_rcp_f32_e32 v228, v228
	v_rcp_f32_e32 v229, v229
	v_nop
	v_mul_f32_e32 v40, v224, v40
	v_mul_f32_e32 v41, v225, v41
	v_mul_f32_e32 v42, v228, v42
	s_setprio 0
	s_setprio 1
	v_mfma_f32_16x16x32_bf16 v[124:127], v[176:179], v[192:195], 0
	v_mul_f32_e32 v43, v229, v43
	v_mul_f32_e32 v40, v44, v40
	v_mul_f32_e32 v41, v45, v41
; __device__ __forceinline__ unsigned cvt_pk_bf16(float lo, float hi) { unsigned r; asm volatile("v_cvt_pk_bf16_f32 %0, %1, %2" : "=v"(r) : "v"(lo), "v"(hi)); return r; }
; __device__ __forceinline__ float siluf_(float x) { return x * sigmoidf_(x); }
; #define PG8_STAGE(bufoff, gbase, voff) do { _Pragma("unroll") for (int _i = 0; _i < 2; ++_i) \
;         __builtin_amdgcn_global_load_lds((const unsigned*)((const char*)(gbase) + (voff)[_i]), (LAS unsigned*)(lds + (bufoff) + ldsw + _i * 8192), 16, 0, 0); } while (0)
; #define PG8_LDA(dst, b, h) do { _Pragma("unroll") for (int m = 0; m < 4; ++m) _Pragma("unroll") for (int k = 0; k < 2; ++k) dst[m][k] = *(const LAS bf16x8*)(lds + PG8_SA(b, h) + aoff + m * 2048 + k * 1024); } while (0)
;     __device__ __forceinline__ void operator()(const f32x4 (&acc)[2][2][4][2], const Unit& u, int wr, int wc, int fr, int fq) const {
;         const int row0 = u.pm * BM + wr * 64 + fr, col0 = u.pn * HALF + wc * 32 + 8 * fq;
;         float rsv[2][4]; load_rstd(rsv, ssq, row0);
; #pragma unroll
;         for (int ai = 0; ai < 2; ++ai)
; #pragma unroll
;             for (int m = 0; m < 4; ++m) { const int row = row0 + ai * HALF + m * 16; bf16_t* rowp = O + (size_t)row * ldc + col0; const float rs = rsv[ai][m];
;                 f32x4 v0, v1;
; #pragma unroll
;                 for (int j = 0; j < 4; ++j) { v0[j] = siluf_(acc[ai][0][m][0][j] * rs) * (acc[ai][1][m][0][j] * rs); v1[j] = siluf_(acc[ai][0][m][1][j] * rs) * (acc[ai][1][m][1][j] * rs); }
;                 u32x4 w; w.x = cvt_pk_bf16(v0[0], v0[1]); w.y = cvt_pk_bf16(v0[2], v0[3]); w.z = cvt_pk_bf16(v1[0], v1[1]); w.w = cvt_pk_bf16(v1[2], v1[3]);
;                 *(u32x4*)rowp = w; }
; template <class Epi, bool ALIGN_EPI>
; __device__ __forceinline__ void gemm_phase(LAS unsigned char* lds, const Gemm g, const StaticOrder& S, const Epi& E, const int tid) {
;     ...
;             PG8_LDB(B0, 0, 0); PG8_LDB(B1, 0, 1); PG8_SCHED; PG8_LDA(At, 0, 0); PG8_STAGE(PG8_SA(1, 1), a1 + hA, voffA);
;             PG8_WAIT_V(8); PG8_WAIT_L(0); PG8_BAR; PG8_MMA(0, 0, At, B0); PG8_MMA(0, 1, At, B1); PG8_BAR; PG8_SCHED;
;             PG8_LDA(At, 0, 1); PG8_STAGE(PG8_SB(0, 0), b2, voffB); PG8_STAGE(PG8_SB(0, 1), b2 + hB, voffB); PG8_STAGE(PG8_SA(0, 0), a2, voffA);
;             PG8_WAIT_V(8); PG8_WAIT_L(0); PG8_BAR; PG8_MMA(1, 0, At, B0); PG8_MMA(1, 1, At, B1); PG8_BAR; PG8_SCHED;
	v_mul_f32_e32 v42, v46, v42
	v_mul_f32_e32 v43, v47, v43
	v_mul_f32_e32 v32, v239, v32
	v_mul_f32_e32 v33, v239, v33
	v_mul_f32_e32 v34, v239, v34
	v_mul_f32_e32 v35, v239, v35
	v_mul_f32_e32 v36, v239, v36
	v_mul_f32_e32 v37, v239, v37
	v_mul_f32_e32 v38, v239, v38
	v_mul_f32_e32 v39, v239, v39
	v_mfma_f32_16x16x32_bf16 v[116:119], v[184:187], v[192:195], 0
	v_mul_f32_e32 v224, s100, v32
	v_mul_f32_e32 v225, s101, v33
	v_mul_f32_e32 v228, s100, v34
	v_mul_f32_e32 v229, s101, v35
	v_exp_f32_e32 v224, v224
	v_exp_f32_e32 v225, v225
	v_exp_f32_e32 v228, v228
	v_exp_f32_e32 v229, v229
	v_add_f32_e32 v224, 1.0, v224
	v_add_f32_e32 v225, 1.0, v225
	v_add_f32_e32 v228, 1.0, v228
	v_add_f32_e32 v229, 1.0, v229
	v_rcp_f32_e32 v224, v224
	v_mfma_f32_16x16x32_bf16 v[108:111], v[176:179], v[200:203], 0
	v_rcp_f32_e32 v225, v225
	v_rcp_f32_e32 v228, v228
	v_rcp_f32_e32 v229, v229
	v_nop
	v_mul_f32_e32 v32, v224, v32
	v_mul_f32_e32 v33, v225, v33
	v_mul_f32_e32 v34, v228, v34
	v_mul_f32_e32 v35, v229, v35
	v_mul_f32_e32 v32, v36, v32
	v_mul_f32_e32 v33, v37, v33
	v_mul_f32_e32 v34, v38, v34
	v_mul_f32_e32 v35, v39, v35
	v_cvt_pk_bf16_f32 v40, v40, v41
	v_mfma_f32_16x16x32_bf16 v[100:103], v[184:187], v[200:203], 0
	v_cvt_pk_bf16_f32 v41, v42, v43
	v_cvt_pk_bf16_f32 v42, v32, v33
	v_cvt_pk_bf16_f32 v43, v34, v35
	global_store_dwordx4 v[232:233], v[40:43], off
	v_lshl_add_u64 v[232:233], v[232:233], 0, s[98:99]
	v_mul_f32_e32 v24, v230, v24
	v_mul_f32_e32 v25, v230, v25
	v_mul_f32_e32 v26, v230, v26
	v_mul_f32_e32 v27, v230, v27
	v_mul_f32_e32 v28, v230, v28
	v_mul_f32_e32 v29, v230, v29
	v_mul_f32_e32 v30, v230, v30
	v_mul_f32_e32 v31, v230, v31
	v_mfma_f32_16x16x32_bf16 v[92:95], v[176:179], v[208:211], 0
	v_mul_f32_e32 v224, s100, v24
	v_mul_f32_e32 v225, s101, v25
	v_mul_f32_e32 v228, s100, v26
	v_mul_f32_e32 v229, s101, v27
	v_exp_f32_e32 v224, v224
	v_exp_f32_e32 v225, v225
	v_exp_f32_e32 v228, v228
	v_exp_f32_e32 v229, v229
	v_add_f32_e32 v224, 1.0, v224
	v_add_f32_e32 v225, 1.0, v225
	v_add_f32_e32 v228, 1.0, v228
	v_add_f32_e32 v229, 1.0, v229
	v_rcp_f32_e32 v224, v224
	v_mfma_f32_16x16x32_bf16 v[84:87], v[184:187], v[208:211], 0
	v_rcp_f32_e32 v225, v225
	v_rcp_f32_e32 v228, v228
	v_rcp_f32_e32 v229, v229
	v_nop
	v_mul_f32_e32 v24, v224, v24
	v_mul_f32_e32 v25, v225, v25
	v_mul_f32_e32 v26, v228, v26
	v_mul_f32_e32 v27, v229, v27
	v_mul_f32_e32 v24, v28, v24
	v_mul_f32_e32 v25, v29, v25
	v_mul_f32_e32 v26, v30, v26
	v_mul_f32_e32 v27, v31, v27
	v_mul_f32_e32 v16, v230, v16
	v_mfma_f32_16x16x32_bf16 v[76:79], v[176:179], v[216:219], 0
	v_mul_f32_e32 v17, v230, v17
	v_mul_f32_e32 v18, v230, v18
	v_mul_f32_e32 v19, v230, v19
	v_mul_f32_e32 v20, v230, v20
	v_mul_f32_e32 v21, v230, v21
	v_mul_f32_e32 v22, v230, v22
	v_mul_f32_e32 v23, v230, v23
	v_mul_f32_e32 v224, s100, v16
	v_mul_f32_e32 v225, s101, v17
	v_mul_f32_e32 v228, s100, v18
	v_mul_f32_e32 v229, s101, v19
	v_exp_f32_e32 v224, v224
	v_exp_f32_e32 v225, v225
	v_mfma_f32_16x16x32_bf16 v[68:71], v[184:187], v[216:219], 0
	v_exp_f32_e32 v228, v228
	v_exp_f32_e32 v229, v229
	v_add_f32_e32 v224, 1.0, v224
	v_add_f32_e32 v225, 1.0, v225
	v_add_f32_e32 v228, 1.0, v228
	v_add_f32_e32 v229, 1.0, v229
	v_rcp_f32_e32 v224, v224
	v_rcp_f32_e32 v225, v225
	v_rcp_f32_e32 v228, v228
	v_rcp_f32_e32 v229, v229
	v_nop
	v_mul_f32_e32 v16, v224, v16
	v_mul_f32_e32 v17, v225, v17
	v_mfma_f32_16x16x32_bf16 v[124:127], v[180:183], v[196:199], v[124:127]
	v_mul_f32_e32 v18, v228, v18
	v_mul_f32_e32 v19, v229, v19
	v_mul_f32_e32 v16, v20, v16
	v_mul_f32_e32 v17, v21, v17
	v_mul_f32_e32 v18, v22, v18
	v_mul_f32_e32 v19, v23, v19
	v_cvt_pk_bf16_f32 v24, v24, v25
	v_cvt_pk_bf16_f32 v25, v26, v27
	v_cvt_pk_bf16_f32 v26, v16, v17
	v_cvt_pk_bf16_f32 v27, v18, v19
	global_store_dwordx4 v[232:233], v[24:27], off
	v_lshl_add_u64 v[232:233], v[232:233], 0, s[98:99]
	v_mul_f32_e32 v8, v231, v8
	v_mfma_f32_16x16x32_bf16 v[116:119], v[188:191], v[196:199], v[116:119]
	v_mul_f32_e32 v9, v231, v9
	v_mul_f32_e32 v10, v231, v10
	v_mul_f32_e32 v11, v231, v11
	v_mul_f32_e32 v12, v231, v12
	v_mul_f32_e32 v13, v231, v13
	v_mul_f32_e32 v14, v231, v14
	v_mul_f32_e32 v15, v231, v15
	v_mul_f32_e32 v224, s100, v8
	v_mul_f32_e32 v225, s101, v9
	v_mul_f32_e32 v228, s100, v10
	v_mul_f32_e32 v229, s101, v11
	v_exp_f32_e32 v224, v224
	v_exp_f32_e32 v225, v225
	v_mfma_f32_16x16x32_bf16 v[108:111], v[180:183], v[204:207], v[108:111]
	v_exp_f32_e32 v228, v228
	v_exp_f32_e32 v229, v229
	v_add_f32_e32 v224, 1.0, v224
	v_add_f32_e32 v225, 1.0, v225
	v_add_f32_e32 v228, 1.0, v228
	v_add_f32_e32 v229, 1.0, v229
	v_rcp_f32_e32 v224, v224
	v_rcp_f32_e32 v225, v225
	v_rcp_f32_e32 v228, v228
	v_rcp_f32_e32 v229, v229
	v_nop
	v_mul_f32_e32 v8, v224, v8
	v_mul_f32_e32 v9, v225, v9
	v_mfma_f32_16x16x32_bf16 v[100:103], v[188:191], v[204:207], v[100:103]
	v_mul_f32_e32 v10, v228, v10
	v_mul_f32_e32 v11, v229, v11
	v_mul_f32_e32 v8, v12, v8
	v_mul_f32_e32 v9, v13, v9
	v_mul_f32_e32 v10, v14, v10
	v_mul_f32_e32 v11, v15, v11
	v_mul_f32_e32 v4, v231, v4
	v_mul_f32_e32 v5, v231, v5
	v_mul_f32_e32 v6, v231, v6
	v_mul_f32_e32 v7, v231, v7
	v_mul_f32_e32 v0, v231, v0
	v_mul_f32_e32 v1, v231, v1
	v_mul_f32_e32 v2, v231, v2
	v_mfma_f32_16x16x32_bf16 v[92:95], v[180:183], v[212:215], v[92:95]
	v_mul_f32_e32 v3, v231, v3
	v_mul_f32_e32 v224, s100, v4
	v_mul_f32_e32 v225, s101, v5
	v_mul_f32_e32 v228, s100, v6
	v_mul_f32_e32 v229, s101, v7
	v_exp_f32_e32 v224, v224
	v_exp_f32_e32 v225, v225
	v_exp_f32_e32 v228, v228
	v_exp_f32_e32 v229, v229
	v_add_f32_e32 v224, 1.0, v224
	v_add_f32_e32 v225, 1.0, v225
	v_add_f32_e32 v228, 1.0, v228
	v_add_f32_e32 v229, 1.0, v229
	v_mfma_f32_16x16x32_bf16 v[84:87], v[188:191], v[212:215], v[84:87]
	v_rcp_f32_e32 v224, v224
	v_rcp_f32_e32 v225, v225
	v_rcp_f32_e32 v228, v228
	v_rcp_f32_e32 v229, v229
	v_nop
	v_mul_f32_e32 v4, v224, v4
	v_mul_f32_e32 v5, v225, v5
	v_mul_f32_e32 v6, v228, v6
	v_mul_f32_e32 v7, v229, v7
	v_mul_f32_e32 v4, v0, v4
	v_mul_f32_e32 v5, v1, v5
	v_mul_f32_e32 v6, v2, v6
	v_mul_f32_e32 v7, v3, v7
	v_mfma_f32_16x16x32_bf16 v[76:79], v[180:183], v[240:243], v[76:79]
	v_cvt_pk_bf16_f32 v8, v8, v9
	v_cvt_pk_bf16_f32 v9, v10, v11
	v_cvt_pk_bf16_f32 v10, v4, v5
	v_cvt_pk_bf16_f32 v11, v6, v7
	global_store_dwordx4 v[232:233], v[8:11], off
	v_mfma_f32_16x16x32_bf16 v[68:71], v[188:191], v[240:243], v[68:71]
	s_setprio 0
	s_barrier
; #define PG8_STAGE(bufoff, gbase, voff) do { _Pragma("unroll") for (int _i = 0; _i < 2; ++_i) \
;         __builtin_amdgcn_global_load_lds((const unsigned*)((const char*)(gbase) + (voff)[_i]), (LAS unsigned*)(lds + (bufoff) + ldsw + _i * 8192), 16, 0, 0); } while (0)
; #define PG8_LDA(dst, b, h) do { _Pragma("unroll") for (int m = 0; m < 4; ++m) _Pragma("unroll") for (int k = 0; k < 2; ++k) dst[m][k] = *(const LAS bf16x8*)(lds + PG8_SA(b, h) + aoff + m * 2048 + k * 1024); } while (0)
; #define PG8_LDB(dst, b, h) do { _Pragma("unroll") for (int n = 0; n < 2; ++n) _Pragma("unroll") for (int k = 0; k < 2; ++k) dst[n][k] = *(const LAS bf16x8*)(lds + PG8_SB(b, h) + boff + n * 2048 + k * 1024); } while (0)
; #define PG8_MMA(ai, bj, At, Bt) do { __builtin_amdgcn_s_setprio(1); _Pragma("unroll") for (int k = 0; k < 2; ++k) _Pragma("unroll") for (int m = 0; m < 4; ++m) _Pragma("unroll") for (int n = 0; n < 2; ++n) \
;         acc[ai][bj][m][n] = __builtin_amdgcn_mfma_f32_16x16x32_bf16(Bt[n][k], At[m][k], acc[ai][bj][m][n], 0, 0, 0); __builtin_amdgcn_s_setprio(0); } while (0)
; #define PG8_WAIT_V(n) asm volatile("s_waitcnt vmcnt(" #n ")" ::: "memory")
; #define PG8_WAIT_L(n) asm volatile("s_waitcnt lgkmcnt(" #n ")" ::: "memory")
; #define PG8_BAR __builtin_amdgcn_s_barrier()
; #define PG8_SCHED __builtin_amdgcn_sched_barrier(0)
; template <class Epi, bool ALIGN_EPI>
; __device__ __forceinline__ void gemm_phase(LAS unsigned char* lds, const Gemm g, const StaticOrder& S, const Epi& E, const int tid) {
;     ...
;             PG8_LDA(At, 0, 1); PG8_STAGE(PG8_SB(0, 0), b2, voffB); PG8_STAGE(PG8_SB(0, 1), b2 + hB, voffB); PG8_STAGE(PG8_SA(0, 0), a2, voffA);
;             PG8_WAIT_V(8); PG8_WAIT_L(0); PG8_BAR; PG8_MMA(1, 0, At, B0); PG8_MMA(1, 1, At, B1); PG8_BAR; PG8_SCHED;
;             PG8_LDB(B0, 1, 0); PG8_LDB(B1, 1, 1); PG8_SCHED; PG8_LDA(At, 1, 0); PG8_STAGE(PG8_SA(0, 1), a2 + hA, voffA);
;             PG8_WAIT_V(8); PG8_WAIT_L(0); PG8_BAR; PG8_MMA(0, 0, At, B0); PG8_MMA(0, 1, At, B1); PG8_BAR; PG8_SCHED;
	s_add_i32 s65, s33, s45
	v_lshl_add_u64 v[226:227], v[220:221], 0, v[168:169]
	s_mov_b32 m0, s65
	ds_read_b128 v[192:195], v153 offset:16384
	ds_read_b128 v[196:199], v153 offset:17408
	ds_read_b128 v[200:203], v153 offset:18432
	ds_read_b128 v[204:207], v153 offset:19456
	ds_read_b128 v[208:211], v153 offset:20480
	ds_read_b128 v[212:215], v153 offset:21504
	ds_read_b128 v[216:219], v153 offset:22528
	ds_read_b128 v[240:243], v153 offset:23552
	global_load_lds_dwordx4 v[226:227], off
	v_lshl_add_u64 v[244:245], v[220:221], 0, v[128:129]
	s_add_i32 m0, s65, 0x2000
	v_lshl_add_u64 v[220:221], v[220:221], 0, s[12:13]
	s_add_i32 s10, s10, s45
	global_load_lds_dwordx4 v[244:245], off
	v_lshl_add_u64 v[246:247], v[220:221], 0, v[168:169]
	s_mov_b32 m0, s10
	v_lshl_add_u64 v[220:221], v[220:221], 0, v[128:129]
	global_load_lds_dwordx4 v[246:247], off
	s_add_i32 m0, s10, 0x2000
	v_lshl_add_u64 v[248:249], v[166:167], 0, v[132:133]
	global_load_lds_dwordx4 v[220:221], off
	s_mov_b32 m0, s51
	v_lshl_add_u64 v[250:251], v[166:167], 0, v[130:131]
	global_load_lds_dwordx4 v[248:249], off
	s_mov_b32 m0, s52
	s_nop 0
	global_load_lds_dwordx4 v[250:251], off
	s_waitcnt vmcnt(16)
	s_waitcnt lgkmcnt(0)
	s_barrier
	s_setprio 1
	s_waitcnt lgkmcnt(0)
	v_mfma_f32_16x16x32_bf16 v[56:59], v[146:149], v[192:195], 0
	v_mfma_f32_16x16x32_bf16 v[48:51], v[158:161], v[192:195], 0
	v_mfma_f32_16x16x32_bf16 v[40:43], v[146:149], v[200:203], 0
	v_mfma_f32_16x16x32_bf16 v[32:35], v[158:161], v[200:203], 0
	v_mfma_f32_16x16x32_bf16 v[24:27], v[146:149], v[208:211], 0
	v_mfma_f32_16x16x32_bf16 v[16:19], v[158:161], v[208:211], 0
	v_mfma_f32_16x16x32_bf16 v[8:11], v[146:149], v[216:219], 0
	v_mfma_f32_16x16x32_bf16 v[4:7], v[158:161], v[216:219], 0
	v_mfma_f32_16x16x32_bf16 v[56:59], v[154:157], v[196:199], v[56:59]
	v_mfma_f32_16x16x32_bf16 v[48:51], v[162:165], v[196:199], v[48:51]
	v_mfma_f32_16x16x32_bf16 v[40:43], v[154:157], v[204:207], v[40:43]
	v_mfma_f32_16x16x32_bf16 v[32:35], v[162:165], v[204:207], v[32:35]
	v_mfma_f32_16x16x32_bf16 v[24:27], v[154:157], v[212:215], v[24:27]
	v_mfma_f32_16x16x32_bf16 v[16:19], v[162:165], v[212:215], v[16:19]
	v_mfma_f32_16x16x32_bf16 v[8:11], v[154:157], v[240:243], v[8:11]
	v_mfma_f32_16x16x32_bf16 v[4:7], v[162:165], v[240:243], v[4:7]
	s_setprio 0
	s_setprio 1
	v_mfma_f32_16x16x32_bf16 v[60:63], v[176:179], v[192:195], 0
	v_mfma_f32_16x16x32_bf16 v[52:55], v[184:187], v[192:195], 0
	v_mfma_f32_16x16x32_bf16 v[44:47], v[176:179], v[200:203], 0
	v_mfma_f32_16x16x32_bf16 v[36:39], v[184:187], v[200:203], 0
	v_mfma_f32_16x16x32_bf16 v[28:31], v[176:179], v[208:211], 0
	v_mfma_f32_16x16x32_bf16 v[20:23], v[184:187], v[208:211], 0
	v_mfma_f32_16x16x32_bf16 v[12:15], v[176:179], v[216:219], 0
	v_mfma_f32_16x16x32_bf16 v[0:3], v[184:187], v[216:219], 0
	v_mfma_f32_16x16x32_bf16 v[60:63], v[180:183], v[196:199], v[60:63]
	v_mfma_f32_16x16x32_bf16 v[52:55], v[188:191], v[196:199], v[52:55]
	v_mfma_f32_16x16x32_bf16 v[44:47], v[180:183], v[204:207], v[44:47]
	v_mfma_f32_16x16x32_bf16 v[36:39], v[188:191], v[204:207], v[36:39]
	v_mfma_f32_16x16x32_bf16 v[28:31], v[180:183], v[212:215], v[28:31]
	v_mfma_f32_16x16x32_bf16 v[20:23], v[188:191], v[212:215], v[20:23]
	v_mfma_f32_16x16x32_bf16 v[12:15], v[180:183], v[240:243], v[12:15]
	v_mfma_f32_16x16x32_bf16 v[0:3], v[188:191], v[240:243], v[0:3]
	s_setprio 0
	s_barrier
	s_add_i32 s10, 0, 0x18000
	v_add_u32_e32 v150, s10, v151
	s_add_i32 s65, 0, 0x1c000
	ds_read_b128 v[146:149], v150
	ds_read_b128 v[154:157], v150 offset:1024
	ds_read_b128 v[158:161], v150 offset:2048
	ds_read_b128 v[162:165], v150 offset:3072
	v_add_u32_e32 v150, s65, v151
	ds_read_b128 v[176:179], v150
	ds_read_b128 v[180:183], v150 offset:1024
	ds_read_b128 v[184:187], v150 offset:2048
	ds_read_b128 v[188:191], v150 offset:3072
	v_lshl_add_u64 v[166:167], v[166:167], 0, s[94:95]
	s_mov_b32 m0, s53
	v_lshl_add_u64 v[252:253], v[166:167], 0, v[132:133]
	ds_read_b128 v[192:195], v153 offset:32768
	ds_read_b128 v[196:199], v153 offset:33792
	ds_read_b128 v[200:203], v153 offset:34816
	ds_read_b128 v[204:207], v153 offset:35840
	ds_read_b128 v[208:211], v153 offset:36864
	ds_read_b128 v[212:215], v153 offset:37888
	ds_read_b128 v[216:219], v153 offset:38912
	ds_read_b128 v[240:243], v153 offset:39936
	global_load_lds_dwordx4 v[252:253], off
	v_lshl_add_u64 v[166:167], v[166:167], 0, v[130:131]
	s_mov_b32 m0, s54
	s_nop 0
	global_load_lds_dwordx4 v[166:167], off
	s_waitcnt vmcnt(12)
	s_waitcnt lgkmcnt(0)
	s_barrier
; #define PG8_STAGE(bufoff, gbase, voff) do { _Pragma("unroll") for (int _i = 0; _i < 2; ++_i) \
;         __builtin_amdgcn_global_load_lds((const unsigned*)((const char*)(gbase) + (voff)[_i]), (LAS unsigned*)(lds + (bufoff) + ldsw + _i * 8192), 16, 0, 0); } while (0)
; #define PG8_LDA(dst, b, h) do { _Pragma("unroll") for (int m = 0; m < 4; ++m) _Pragma("unroll") for (int k = 0; k < 2; ++k) dst[m][k] = *(const LAS bf16x8*)(lds + PG8_SA(b, h) + aoff + m * 2048 + k * 1024); } while (0)
; #define PG8_LDB(dst, b, h) do { _Pragma("unroll") for (int n = 0; n < 2; ++n) _Pragma("unroll") for (int k = 0; k < 2; ++k) dst[n][k] = *(const LAS bf16x8*)(lds + PG8_SB(b, h) + boff + n * 2048 + k * 1024); } while (0)
; #define PG8_MMA(ai, bj, At, Bt) do { __builtin_amdgcn_s_setprio(1); _Pragma("unroll") for (int k = 0; k < 2; ++k) _Pragma("unroll") for (int m = 0; m < 4; ++m) _Pragma("unroll") for (int n = 0; n < 2; ++n) \
;         acc[ai][bj][m][n] = __builtin_amdgcn_mfma_f32_16x16x32_bf16(Bt[n][k], At[m][k], acc[ai][bj][m][n], 0, 0, 0); __builtin_amdgcn_s_setprio(0); } while (0)
; #define PG8_WAIT_V(n) asm volatile("s_waitcnt vmcnt(" #n ")" ::: "memory")
; #define PG8_WAIT_L(n) asm volatile("s_waitcnt lgkmcnt(" #n ")" ::: "memory")
; #define PG8_BAR __builtin_amdgcn_s_barrier()
; #define PG8_SCHED __builtin_amdgcn_sched_barrier(0)
; template <class Epi, bool ALIGN_EPI>
; __device__ __forceinline__ void gemm_phase(LAS unsigned char* lds, const Gemm g, const StaticOrder& S, const Epi& E, const int tid) {
;     ...
;             PG8_LDB(B0, 1, 0); PG8_LDB(B1, 1, 1); PG8_SCHED; PG8_LDA(At, 1, 0); PG8_STAGE(PG8_SA(0, 1), a2 + hA, voffA);
;             PG8_WAIT_V(8); PG8_WAIT_L(0); PG8_BAR; PG8_MMA(0, 0, At, B0); PG8_MMA(0, 1, At, B1); PG8_BAR; PG8_SCHED;
;             PG8_LDA(At, 1, 1); PG8_STAGE(PG8_SB(1, 0), b3, voffB); PG8_STAGE(PG8_SB(1, 1), b3 + hB, voffB); PG8_STAGE(PG8_SA(1, 0), a3, voffA);
;             PG8_WAIT_V(8); PG8_WAIT_L(0); PG8_BAR; PG8_MMA(1, 0, At, B0); PG8_MMA(1, 1, At, B1); PG8_BAR; PG8_SCHED;
	s_setprio 1
	s_waitcnt lgkmcnt(0)
	v_mfma_f32_16x16x32_bf16 v[120:123], v[146:149], v[192:195], v[120:123]
	v_mfma_f32_16x16x32_bf16 v[112:115], v[158:161], v[192:195], v[112:115]
	v_mfma_f32_16x16x32_bf16 v[104:107], v[146:149], v[200:203], v[104:107]
	v_mfma_f32_16x16x32_bf16 v[96:99], v[158:161], v[200:203], v[96:99]
	v_mfma_f32_16x16x32_bf16 v[88:91], v[146:149], v[208:211], v[88:91]
	v_mfma_f32_16x16x32_bf16 v[80:83], v[158:161], v[208:211], v[80:83]
	v_mfma_f32_16x16x32_bf16 v[72:75], v[146:149], v[216:219], v[72:75]
	v_mfma_f32_16x16x32_bf16 v[64:67], v[158:161], v[216:219], v[64:67]
	v_mfma_f32_16x16x32_bf16 v[120:123], v[154:157], v[196:199], v[120:123]
	v_mfma_f32_16x16x32_bf16 v[112:115], v[162:165], v[196:199], v[112:115]
	v_mfma_f32_16x16x32_bf16 v[104:107], v[154:157], v[204:207], v[104:107]
	v_mfma_f32_16x16x32_bf16 v[96:99], v[162:165], v[204:207], v[96:99]
	v_mfma_f32_16x16x32_bf16 v[88:91], v[154:157], v[212:215], v[88:91]
	v_mfma_f32_16x16x32_bf16 v[80:83], v[162:165], v[212:215], v[80:83]
	v_mfma_f32_16x16x32_bf16 v[72:75], v[154:157], v[240:243], v[72:75]
	v_mfma_f32_16x16x32_bf16 v[64:67], v[162:165], v[240:243], v[64:67]
	s_setprio 0
	s_setprio 1
	v_mfma_f32_16x16x32_bf16 v[124:127], v[176:179], v[192:195], v[124:127]
	v_mfma_f32_16x16x32_bf16 v[116:119], v[184:187], v[192:195], v[116:119]
	v_mfma_f32_16x16x32_bf16 v[108:111], v[176:179], v[200:203], v[108:111]
	v_mfma_f32_16x16x32_bf16 v[100:103], v[184:187], v[200:203], v[100:103]
	v_mfma_f32_16x16x32_bf16 v[92:95], v[176:179], v[208:211], v[92:95]
	v_mfma_f32_16x16x32_bf16 v[84:87], v[184:187], v[208:211], v[84:87]
	v_mfma_f32_16x16x32_bf16 v[76:79], v[176:179], v[216:219], v[76:79]
	v_mfma_f32_16x16x32_bf16 v[68:71], v[184:187], v[216:219], v[68:71]
	v_mfma_f32_16x16x32_bf16 v[124:127], v[180:183], v[196:199], v[124:127]
	v_mfma_f32_16x16x32_bf16 v[116:119], v[188:191], v[196:199], v[116:119]
	v_mfma_f32_16x16x32_bf16 v[108:111], v[180:183], v[204:207], v[108:111]
	v_mfma_f32_16x16x32_bf16 v[100:103], v[188:191], v[204:207], v[100:103]
	v_mfma_f32_16x16x32_bf16 v[92:95], v[180:183], v[212:215], v[92:95]
	v_mfma_f32_16x16x32_bf16 v[84:87], v[188:191], v[212:215], v[84:87]
	v_mfma_f32_16x16x32_bf16 v[76:79], v[180:183], v[240:243], v[76:79]
	v_mfma_f32_16x16x32_bf16 v[68:71], v[188:191], v[240:243], v[68:71]
	s_setprio 0
	s_barrier
	s_add_i32 s10, s10, s45
	v_lshl_add_u64 v[166:167], v[226:227], 0, s[92:93]
	s_mov_b32 m0, s10
	ds_read_b128 v[192:195], v153 offset:49152
	ds_read_b128 v[196:199], v153 offset:50176
	ds_read_b128 v[200:203], v153 offset:51200
	ds_read_b128 v[204:207], v153 offset:52224
	ds_read_b128 v[208:211], v153 offset:53248
	ds_read_b128 v[212:215], v153 offset:54272
	ds_read_b128 v[216:219], v153 offset:55296
	ds_read_b128 v[240:243], v153 offset:56320
	global_load_lds_dwordx4 v[166:167], off
	v_lshl_add_u64 v[166:167], v[244:245], 0, s[92:93]
	s_add_i32 m0, s10, 0x2000
	s_add_i32 s10, s65, s45
	global_load_lds_dwordx4 v[166:167], off
	v_lshl_add_u64 v[166:167], v[246:247], 0, s[92:93]
	s_mov_b32 m0, s10
	s_nop 0
	global_load_lds_dwordx4 v[166:167], off
	v_lshl_add_u64 v[166:167], v[220:221], 0, s[92:93]
	s_add_i32 m0, s10, 0x2000
	s_nop 0
	global_load_lds_dwordx4 v[166:167], off
	v_lshl_add_u64 v[166:167], v[248:249], 0, s[92:93]
	s_mov_b32 m0, s56
	s_nop 0
	global_load_lds_dwordx4 v[166:167], off
	v_lshl_add_u64 v[166:167], v[250:251], 0, s[92:93]
	s_mov_b32 m0, s57
	s_nop 0
	global_load_lds_dwordx4 v[166:167], off
	s_waitcnt vmcnt(8)
	s_waitcnt lgkmcnt(0)
	s_barrier
	s_setprio 1
	s_waitcnt lgkmcnt(0)
	v_mfma_f32_16x16x32_bf16 v[56:59], v[146:149], v[192:195], v[56:59]
	v_mfma_f32_16x16x32_bf16 v[48:51], v[158:161], v[192:195], v[48:51]
	v_mfma_f32_16x16x32_bf16 v[40:43], v[146:149], v[200:203], v[40:43]
	v_mfma_f32_16x16x32_bf16 v[32:35], v[158:161], v[200:203], v[32:35]
	v_mfma_f32_16x16x32_bf16 v[24:27], v[146:149], v[208:211], v[24:27]
	v_mfma_f32_16x16x32_bf16 v[16:19], v[158:161], v[208:211], v[16:19]
	v_mfma_f32_16x16x32_bf16 v[8:11], v[146:149], v[216:219], v[8:11]
	v_mfma_f32_16x16x32_bf16 v[4:7], v[158:161], v[216:219], v[4:7]
	v_mfma_f32_16x16x32_bf16 v[56:59], v[154:157], v[196:199], v[56:59]
	v_mfma_f32_16x16x32_bf16 v[48:51], v[162:165], v[196:199], v[48:51]
	v_mfma_f32_16x16x32_bf16 v[40:43], v[154:157], v[204:207], v[40:43]
	v_mfma_f32_16x16x32_bf16 v[32:35], v[162:165], v[204:207], v[32:35]
	v_mfma_f32_16x16x32_bf16 v[24:27], v[154:157], v[212:215], v[24:27]
	v_mfma_f32_16x16x32_bf16 v[16:19], v[162:165], v[212:215], v[16:19]
	v_mfma_f32_16x16x32_bf16 v[8:11], v[154:157], v[240:243], v[8:11]
	v_mfma_f32_16x16x32_bf16 v[4:7], v[162:165], v[240:243], v[4:7]
	s_setprio 0
	s_setprio 1
	v_mfma_f32_16x16x32_bf16 v[60:63], v[176:179], v[192:195], v[60:63]
	v_mfma_f32_16x16x32_bf16 v[52:55], v[184:187], v[192:195], v[52:55]
	v_mfma_f32_16x16x32_bf16 v[44:47], v[176:179], v[200:203], v[44:47]
	v_mfma_f32_16x16x32_bf16 v[36:39], v[184:187], v[200:203], v[36:39]
	v_mfma_f32_16x16x32_bf16 v[28:31], v[176:179], v[208:211], v[28:31]
	v_mfma_f32_16x16x32_bf16 v[20:23], v[184:187], v[208:211], v[20:23]
	v_mfma_f32_16x16x32_bf16 v[12:15], v[176:179], v[216:219], v[12:15]
	v_mfma_f32_16x16x32_bf16 v[0:3], v[184:187], v[216:219], v[0:3]
	v_mfma_f32_16x16x32_bf16 v[60:63], v[180:183], v[196:199], v[60:63]
	v_mfma_f32_16x16x32_bf16 v[52:55], v[188:191], v[196:199], v[52:55]
	v_mfma_f32_16x16x32_bf16 v[44:47], v[180:183], v[204:207], v[44:47]
	v_mfma_f32_16x16x32_bf16 v[36:39], v[188:191], v[204:207], v[36:39]
	v_mfma_f32_16x16x32_bf16 v[28:31], v[180:183], v[212:215], v[28:31]
	v_mfma_f32_16x16x32_bf16 v[20:23], v[188:191], v[212:215], v[20:23]
	v_mfma_f32_16x16x32_bf16 v[12:15], v[180:183], v[240:243], v[12:15]
	v_mfma_f32_16x16x32_bf16 v[0:3], v[188:191], v[240:243], v[0:3]
	s_setprio 0
	s_barrier
	v_lshl_add_u64 v[142:143], v[142:143], 0, s[80:81]
	v_lshl_add_u64 v[144:145], v[144:145], 0, s[80:81]
	s_mov_b32 s10, s11
	s_cmp_eq_u32 s10, s58
	s_cbranch_scc1 .Lgu_last
	s_branch .LBB0_308

; #define PG8_STAGE(bufoff, gbase, voff) do { _Pragma("unroll") for (int _i = 0; _i < 2; ++_i) \
;         __builtin_amdgcn_global_load_lds((const unsigned*)((const char*)(gbase) + (voff)[_i]), (LAS unsigned*)(lds + (bufoff) + ldsw + _i * 8192), 16, 0, 0); } while (0)
; #define PG8_LDA(dst, b, h) do { _Pragma("unroll") for (int m = 0; m < 4; ++m) _Pragma("unroll") for (int k = 0; k < 2; ++k) dst[m][k] = *(const LAS bf16x8*)(lds + PG8_SA(b, h) + aoff + m * 2048 + k * 1024); } while (0)
; #define PG8_LDB(dst, b, h) do { _Pragma("unroll") for (int n = 0; n < 2; ++n) _Pragma("unroll") for (int k = 0; k < 2; ++k) dst[n][k] = *(const LAS bf16x8*)(lds + PG8_SB(b, h) + boff + n * 2048 + k * 1024); } while (0)
; #define PG8_MMA(ai, bj, At, Bt) do { __builtin_amdgcn_s_setprio(1); _Pragma("unroll") for (int k = 0; k < 2; ++k) _Pragma("unroll") for (int m = 0; m < 4; ++m) _Pragma("unroll") for (int n = 0; n < 2; ++n) \
;         acc[ai][bj][m][n] = __builtin_amdgcn_mfma_f32_16x16x32_bf16(Bt[n][k], At[m][k], acc[ai][bj][m][n], 0, 0, 0); __builtin_amdgcn_s_setprio(0); } while (0)
; #define PG8_WAIT_V(n) asm volatile("s_waitcnt vmcnt(" #n ")" ::: "memory")
; template <class Epi, bool ALIGN_EPI>
; __device__ __forceinline__ void gemm_phase(LAS unsigned char* lds, const Gemm g, const StaticOrder& S, const Epi& E, const int tid) {
;     ...
;         const char* nA = has_next ? (const char*)g.A + (size_t)nxt.pm * tA + (size_t)nxt.pn * g.apn * 2 : cA; const char* nB = has_next ? (const char*)g.Bt + (size_t)nxt.pn * tB : cB;
;         for (int t = 0; t < nt; t += 2) {
;             const bool last = (t == nt - 2);
;             const char* a1 = cA + (size_t)(t + 1) * kstep;
;             const char* a2 = last ? nA : cA + (size_t)(t + 2) * kstep; const char* b2 = last ? nB : cB + (size_t)(t + 2) * kstep;
;             const char* a3 = a2 + kstep; const char* b3 = b2 + kstep;
;             PG8_LDB(B0, 0, 0); PG8_LDB(B1, 0, 1); PG8_SCHED; PG8_LDA(At, 0, 0); PG8_STAGE(PG8_SA(1, 1), a1 + hA, voffA);
;             PG8_WAIT_V(8); PG8_WAIT_L(0); PG8_BAR; PG8_MMA(0, 0, At, B0); PG8_MMA(0, 1, At, B1); PG8_BAR; PG8_SCHED;
;             PG8_LDA(At, 0, 1); PG8_STAGE(PG8_SB(0, 0), b2, voffB); PG8_STAGE(PG8_SB(0, 1), b2 + hB, voffB); PG8_STAGE(PG8_SA(0, 0), a2, voffA);
;             PG8_WAIT_V(8); PG8_WAIT_L(0); PG8_BAR; PG8_MMA(1, 0, At, B0); PG8_MMA(1, 1, At, B1); PG8_BAR; PG8_SCHED;
.Lgu_last:
	s_add_i32 s11, s10, 2
	s_cmp_eq_u32 s58, s10
	v_lshl_add_u64 v[146:147], v[142:143], 0, s[92:93]
	s_cselect_b64 vcc, -1, 0
	v_add_u32_e32 v150, s33, v151
	s_add_i32 s10, 0, 0x14000
	v_cndmask_b32_e32 v167, v147, v139, vcc
	v_cndmask_b32_e32 v166, v146, v138, vcc
	ds_read_b128 v[146:149], v150
	ds_read_b128 v[154:157], v150 offset:1024
	ds_read_b128 v[158:161], v150 offset:2048
	ds_read_b128 v[162:165], v150 offset:3072
	v_add_u32_e32 v150, s10, v151
	ds_read_b128 v[176:179], v150
	ds_read_b128 v[180:183], v150 offset:1024
	ds_read_b128 v[184:187], v150 offset:2048
	ds_read_b128 v[188:191], v150 offset:3072
	v_cndmask_b32_e32 v221, v145, v141, vcc
	v_cndmask_b32_e32 v220, v144, v140, vcc
	v_lshl_add_u64 v[226:227], v[142:143], 0, v[134:135]
	s_add_i32 m0, s51, 0xc000
	ds_read_b128 v[192:195], v153
	ds_read_b128 v[196:199], v153 offset:1024
	ds_read_b128 v[200:203], v153 offset:2048
	ds_read_b128 v[204:207], v153 offset:3072
	ds_read_b128 v[208:211], v153 offset:4096
	ds_read_b128 v[212:215], v153 offset:5120
	ds_read_b128 v[216:219], v153 offset:6144
	ds_read_b128 v[240:243], v153 offset:7168
	global_load_lds_dwordx4 v[226:227], off
	v_lshl_add_u64 v[226:227], v[142:143], 0, v[136:137]
	s_add_i32 m0, s51, 0xe000
	s_nop 0
	global_load_lds_dwordx4 v[226:227], off
	s_waitcnt vmcnt(8)
	s_waitcnt lgkmcnt(0)
	s_barrier
	s_setprio 1
	s_waitcnt lgkmcnt(0)
	v_mfma_f32_16x16x32_bf16 v[120:123], v[146:149], v[192:195], v[120:123]
	v_mfma_f32_16x16x32_bf16 v[112:115], v[158:161], v[192:195], v[112:115]
	v_mfma_f32_16x16x32_bf16 v[104:107], v[146:149], v[200:203], v[104:107]
	v_mfma_f32_16x16x32_bf16 v[96:99], v[158:161], v[200:203], v[96:99]
	v_mfma_f32_16x16x32_bf16 v[88:91], v[146:149], v[208:211], v[88:91]
	v_mfma_f32_16x16x32_bf16 v[80:83], v[158:161], v[208:211], v[80:83]
	v_mfma_f32_16x16x32_bf16 v[72:75], v[146:149], v[216:219], v[72:75]
	v_mfma_f32_16x16x32_bf16 v[64:67], v[158:161], v[216:219], v[64:67]
	v_mfma_f32_16x16x32_bf16 v[120:123], v[154:157], v[196:199], v[120:123]
	v_mfma_f32_16x16x32_bf16 v[112:115], v[162:165], v[196:199], v[112:115]
	v_mfma_f32_16x16x32_bf16 v[104:107], v[154:157], v[204:207], v[104:107]
	v_mfma_f32_16x16x32_bf16 v[96:99], v[162:165], v[204:207], v[96:99]
	v_mfma_f32_16x16x32_bf16 v[88:91], v[154:157], v[212:215], v[88:91]
	v_mfma_f32_16x16x32_bf16 v[80:83], v[162:165], v[212:215], v[80:83]
	v_mfma_f32_16x16x32_bf16 v[72:75], v[154:157], v[240:243], v[72:75]
	v_mfma_f32_16x16x32_bf16 v[64:67], v[162:165], v[240:243], v[64:67]
	s_setprio 0
	s_setprio 1
	v_mfma_f32_16x16x32_bf16 v[124:127], v[176:179], v[192:195], v[124:127]
	v_mfma_f32_16x16x32_bf16 v[116:119], v[184:187], v[192:195], v[116:119]
	v_mfma_f32_16x16x32_bf16 v[108:111], v[176:179], v[200:203], v[108:111]
	v_mfma_f32_16x16x32_bf16 v[100:103], v[184:187], v[200:203], v[100:103]
	v_mfma_f32_16x16x32_bf16 v[92:95], v[176:179], v[208:211], v[92:95]
	v_mfma_f32_16x16x32_bf16 v[84:87], v[184:187], v[208:211], v[84:87]
	v_mfma_f32_16x16x32_bf16 v[76:79], v[176:179], v[216:219], v[76:79]
	v_mfma_f32_16x16x32_bf16 v[68:71], v[184:187], v[216:219], v[68:71]
	v_mfma_f32_16x16x32_bf16 v[124:127], v[180:183], v[196:199], v[124:127]
	v_mfma_f32_16x16x32_bf16 v[116:119], v[188:191], v[196:199], v[116:119]
	v_mfma_f32_16x16x32_bf16 v[108:111], v[180:183], v[204:207], v[108:111]
	v_mfma_f32_16x16x32_bf16 v[100:103], v[188:191], v[204:207], v[100:103]
	v_mfma_f32_16x16x32_bf16 v[92:95], v[180:183], v[212:215], v[92:95]
	v_mfma_f32_16x16x32_bf16 v[84:87], v[188:191], v[212:215], v[84:87]
	v_mfma_f32_16x16x32_bf16 v[76:79], v[180:183], v[240:243], v[76:79]
	v_mfma_f32_16x16x32_bf16 v[68:71], v[188:191], v[240:243], v[68:71]
	s_setprio 0
	s_barrier
	s_add_i32 s65, s33, s45
	v_lshl_add_u64 v[226:227], v[220:221], 0, v[168:169]
	s_mov_b32 m0, s65
	ds_read_b128 v[192:195], v153 offset:16384
	ds_read_b128 v[196:199], v153 offset:17408
	ds_read_b128 v[200:203], v153 offset:18432
	ds_read_b128 v[204:207], v153 offset:19456
	ds_read_b128 v[208:211], v153 offset:20480
	ds_read_b128 v[212:215], v153 offset:21504
	ds_read_b128 v[216:219], v153 offset:22528
	ds_read_b128 v[240:243], v153 offset:23552
	global_load_lds_dwordx4 v[226:227], off
	v_lshl_add_u64 v[244:245], v[220:221], 0, v[128:129]
	s_add_i32 m0, s65, 0x2000
	v_lshl_add_u64 v[220:221], v[220:221], 0, s[12:13]
	s_add_i32 s10, s10, s45
	global_load_lds_dwordx4 v[244:245], off
	v_lshl_add_u64 v[246:247], v[220:221], 0, v[168:169]
	s_mov_b32 m0, s10
	v_lshl_add_u64 v[220:221], v[220:221], 0, v[128:129]
	global_load_lds_dwordx4 v[246:247], off
	s_add_i32 m0, s10, 0x2000
	v_lshl_add_u64 v[248:249], v[166:167], 0, v[132:133]
	global_load_lds_dwordx4 v[220:221], off
	s_mov_b32 m0, s51
	v_lshl_add_u64 v[250:251], v[166:167], 0, v[130:131]
	global_load_lds_dwordx4 v[248:249], off
	s_mov_b32 m0, s52
	s_nop 0
	global_load_lds_dwordx4 v[250:251], off
	s_waitcnt vmcnt(8)
	s_waitcnt lgkmcnt(0)
	s_barrier
; #define PG8_STAGE(bufoff, gbase, voff) do { _Pragma("unroll") for (int _i = 0; _i < 2; ++_i) \
;         __builtin_amdgcn_global_load_lds((const unsigned*)((const char*)(gbase) + (voff)[_i]), (LAS unsigned*)(lds + (bufoff) + ldsw + _i * 8192), 16, 0, 0); } while (0)
; #define PG8_LDA(dst, b, h) do { _Pragma("unroll") for (int m = 0; m < 4; ++m) _Pragma("unroll") for (int k = 0; k < 2; ++k) dst[m][k] = *(const LAS bf16x8*)(lds + PG8_SA(b, h) + aoff + m * 2048 + k * 1024); } while (0)
; #define PG8_LDB(dst, b, h) do { _Pragma("unroll") for (int n = 0; n < 2; ++n) _Pragma("unroll") for (int k = 0; k < 2; ++k) dst[n][k] = *(const LAS bf16x8*)(lds + PG8_SB(b, h) + boff + n * 2048 + k * 1024); } while (0)
; #define PG8_MMA(ai, bj, At, Bt) do { __builtin_amdgcn_s_setprio(1); _Pragma("unroll") for (int k = 0; k < 2; ++k) _Pragma("unroll") for (int m = 0; m < 4; ++m) _Pragma("unroll") for (int n = 0; n < 2; ++n) \
;         acc[ai][bj][m][n] = __builtin_amdgcn_mfma_f32_16x16x32_bf16(Bt[n][k], At[m][k], acc[ai][bj][m][n], 0, 0, 0); __builtin_amdgcn_s_setprio(0); } while (0)
; #define PG8_WAIT_V(n) asm volatile("s_waitcnt vmcnt(" #n ")" ::: "memory")
; #define PG8_WAIT_L(n) asm volatile("s_waitcnt lgkmcnt(" #n ")" ::: "memory")
; #define PG8_BAR __builtin_amdgcn_s_barrier()
; #define PG8_SCHED __builtin_amdgcn_sched_barrier(0)
; template <class Epi, bool ALIGN_EPI>
; __device__ __forceinline__ void gemm_phase(LAS unsigned char* lds, const Gemm g, const StaticOrder& S, const Epi& E, const int tid) {
;     ...
;             PG8_LDA(At, 0, 1); PG8_STAGE(PG8_SB(0, 0), b2, voffB); PG8_STAGE(PG8_SB(0, 1), b2 + hB, voffB); PG8_STAGE(PG8_SA(0, 0), a2, voffA);
;             PG8_WAIT_V(8); PG8_WAIT_L(0); PG8_BAR; PG8_MMA(1, 0, At, B0); PG8_MMA(1, 1, At, B1); PG8_BAR; PG8_SCHED;
;             PG8_LDB(B0, 1, 0); PG8_LDB(B1, 1, 1); PG8_SCHED; PG8_LDA(At, 1, 0); PG8_STAGE(PG8_SA(0, 1), a2 + hA, voffA);
;             PG8_WAIT_V(8); PG8_WAIT_L(0); PG8_BAR; PG8_MMA(0, 0, At, B0); PG8_MMA(0, 1, At, B1); PG8_BAR; PG8_SCHED;
;             PG8_LDA(At, 1, 1); PG8_STAGE(PG8_SB(1, 0), b3, voffB); PG8_STAGE(PG8_SB(1, 1), b3 + hB, voffB); PG8_STAGE(PG8_SA(1, 0), a3, voffA);
;             PG8_WAIT_V(8); PG8_WAIT_L(0); PG8_BAR; PG8_MMA(1, 0, At, B0); PG8_MMA(1, 1, At, B1); PG8_BAR; PG8_SCHED;
	s_setprio 1
	s_waitcnt lgkmcnt(0)
	v_mfma_f32_16x16x32_bf16 v[56:59], v[146:149], v[192:195], v[56:59]
	v_mfma_f32_16x16x32_bf16 v[48:51], v[158:161], v[192:195], v[48:51]
	v_mfma_f32_16x16x32_bf16 v[40:43], v[146:149], v[200:203], v[40:43]
	v_mfma_f32_16x16x32_bf16 v[32:35], v[158:161], v[200:203], v[32:35]
	v_mfma_f32_16x16x32_bf16 v[24:27], v[146:149], v[208:211], v[24:27]
	v_mfma_f32_16x16x32_bf16 v[16:19], v[158:161], v[208:211], v[16:19]
	v_mfma_f32_16x16x32_bf16 v[8:11], v[146:149], v[216:219], v[8:11]
	v_mfma_f32_16x16x32_bf16 v[4:7], v[158:161], v[216:219], v[4:7]
	v_mfma_f32_16x16x32_bf16 v[56:59], v[154:157], v[196:199], v[56:59]
	v_mfma_f32_16x16x32_bf16 v[48:51], v[162:165], v[196:199], v[48:51]
	v_mfma_f32_16x16x32_bf16 v[40:43], v[154:157], v[204:207], v[40:43]
	v_mfma_f32_16x16x32_bf16 v[32:35], v[162:165], v[204:207], v[32:35]
	v_mfma_f32_16x16x32_bf16 v[24:27], v[154:157], v[212:215], v[24:27]
	v_mfma_f32_16x16x32_bf16 v[16:19], v[162:165], v[212:215], v[16:19]
	v_mfma_f32_16x16x32_bf16 v[8:11], v[154:157], v[240:243], v[8:11]
	v_mfma_f32_16x16x32_bf16 v[4:7], v[162:165], v[240:243], v[4:7]
	s_setprio 0
	s_setprio 1
	v_mfma_f32_16x16x32_bf16 v[60:63], v[176:179], v[192:195], v[60:63]
	v_mfma_f32_16x16x32_bf16 v[52:55], v[184:187], v[192:195], v[52:55]
	v_mfma_f32_16x16x32_bf16 v[44:47], v[176:179], v[200:203], v[44:47]
	v_mfma_f32_16x16x32_bf16 v[36:39], v[184:187], v[200:203], v[36:39]
	v_mfma_f32_16x16x32_bf16 v[28:31], v[176:179], v[208:211], v[28:31]
	v_mfma_f32_16x16x32_bf16 v[20:23], v[184:187], v[208:211], v[20:23]
	v_mfma_f32_16x16x32_bf16 v[12:15], v[176:179], v[216:219], v[12:15]
	v_mfma_f32_16x16x32_bf16 v[0:3], v[184:187], v[216:219], v[0:3]
	v_mfma_f32_16x16x32_bf16 v[60:63], v[180:183], v[196:199], v[60:63]
	v_mfma_f32_16x16x32_bf16 v[52:55], v[188:191], v[196:199], v[52:55]
	v_mfma_f32_16x16x32_bf16 v[44:47], v[180:183], v[204:207], v[44:47]
	v_mfma_f32_16x16x32_bf16 v[36:39], v[188:191], v[204:207], v[36:39]
	v_mfma_f32_16x16x32_bf16 v[28:31], v[180:183], v[212:215], v[28:31]
	v_mfma_f32_16x16x32_bf16 v[20:23], v[188:191], v[212:215], v[20:23]
	v_mfma_f32_16x16x32_bf16 v[12:15], v[180:183], v[240:243], v[12:15]
	v_mfma_f32_16x16x32_bf16 v[0:3], v[188:191], v[240:243], v[0:3]
	s_setprio 0
	s_barrier
	s_add_i32 s10, 0, 0x18000
	v_add_u32_e32 v150, s10, v151
	s_add_i32 s65, 0, 0x1c000
	ds_read_b128 v[146:149], v150
	ds_read_b128 v[154:157], v150 offset:1024
	ds_read_b128 v[158:161], v150 offset:2048
	ds_read_b128 v[162:165], v150 offset:3072
	v_add_u32_e32 v150, s65, v151
	ds_read_b128 v[176:179], v150
	ds_read_b128 v[180:183], v150 offset:1024
	ds_read_b128 v[184:187], v150 offset:2048
	ds_read_b128 v[188:191], v150 offset:3072
	v_lshl_add_u64 v[166:167], v[166:167], 0, s[94:95]
	s_mov_b32 m0, s53
	v_lshl_add_u64 v[252:253], v[166:167], 0, v[132:133]
	ds_read_b128 v[192:195], v153 offset:32768
	ds_read_b128 v[196:199], v153 offset:33792
	ds_read_b128 v[200:203], v153 offset:34816
	ds_read_b128 v[204:207], v153 offset:35840
	ds_read_b128 v[208:211], v153 offset:36864
	ds_read_b128 v[212:215], v153 offset:37888
	ds_read_b128 v[216:219], v153 offset:38912
	ds_read_b128 v[240:243], v153 offset:39936
	global_load_lds_dwordx4 v[252:253], off
	v_lshl_add_u64 v[166:167], v[166:167], 0, v[130:131]
	s_mov_b32 m0, s54
	s_nop 0
	global_load_lds_dwordx4 v[166:167], off
	s_waitcnt vmcnt(8)
	s_waitcnt lgkmcnt(0)
	s_barrier
	s_setprio 1
	s_waitcnt lgkmcnt(0)
	v_mfma_f32_16x16x32_bf16 v[120:123], v[146:149], v[192:195], v[120:123]
	v_mfma_f32_16x16x32_bf16 v[112:115], v[158:161], v[192:195], v[112:115]
	v_mfma_f32_16x16x32_bf16 v[104:107], v[146:149], v[200:203], v[104:107]
	v_mfma_f32_16x16x32_bf16 v[96:99], v[158:161], v[200:203], v[96:99]
	v_mfma_f32_16x16x32_bf16 v[88:91], v[146:149], v[208:211], v[88:91]
	v_mfma_f32_16x16x32_bf16 v[80:83], v[158:161], v[208:211], v[80:83]
	v_mfma_f32_16x16x32_bf16 v[72:75], v[146:149], v[216:219], v[72:75]
	v_mfma_f32_16x16x32_bf16 v[64:67], v[158:161], v[216:219], v[64:67]
	v_mfma_f32_16x16x32_bf16 v[120:123], v[154:157], v[196:199], v[120:123]
	v_mfma_f32_16x16x32_bf16 v[112:115], v[162:165], v[196:199], v[112:115]
	v_mfma_f32_16x16x32_bf16 v[104:107], v[154:157], v[204:207], v[104:107]
	v_mfma_f32_16x16x32_bf16 v[96:99], v[162:165], v[204:207], v[96:99]
	v_mfma_f32_16x16x32_bf16 v[88:91], v[154:157], v[212:215], v[88:91]
	v_mfma_f32_16x16x32_bf16 v[80:83], v[162:165], v[212:215], v[80:83]
	v_mfma_f32_16x16x32_bf16 v[72:75], v[154:157], v[240:243], v[72:75]
	v_mfma_f32_16x16x32_bf16 v[64:67], v[162:165], v[240:243], v[64:67]
	s_setprio 0
	s_setprio 1
	v_mfma_f32_16x16x32_bf16 v[124:127], v[176:179], v[192:195], v[124:127]
	v_mfma_f32_16x16x32_bf16 v[116:119], v[184:187], v[192:195], v[116:119]
	v_mfma_f32_16x16x32_bf16 v[108:111], v[176:179], v[200:203], v[108:111]
	v_mfma_f32_16x16x32_bf16 v[100:103], v[184:187], v[200:203], v[100:103]
	v_mfma_f32_16x16x32_bf16 v[92:95], v[176:179], v[208:211], v[92:95]
	v_mfma_f32_16x16x32_bf16 v[84:87], v[184:187], v[208:211], v[84:87]
	v_mfma_f32_16x16x32_bf16 v[76:79], v[176:179], v[216:219], v[76:79]
	v_mfma_f32_16x16x32_bf16 v[68:71], v[184:187], v[216:219], v[68:71]
	v_mfma_f32_16x16x32_bf16 v[124:127], v[180:183], v[196:199], v[124:127]
	v_mfma_f32_16x16x32_bf16 v[116:119], v[188:191], v[196:199], v[116:119]
	v_mfma_f32_16x16x32_bf16 v[108:111], v[180:183], v[204:207], v[108:111]
	v_mfma_f32_16x16x32_bf16 v[100:103], v[188:191], v[204:207], v[100:103]
	v_mfma_f32_16x16x32_bf16 v[92:95], v[180:183], v[212:215], v[92:95]
	v_mfma_f32_16x16x32_bf16 v[84:87], v[188:191], v[212:215], v[84:87]
	v_mfma_f32_16x16x32_bf16 v[76:79], v[180:183], v[240:243], v[76:79]
	v_mfma_f32_16x16x32_bf16 v[68:71], v[188:191], v[240:243], v[68:71]
	s_setprio 0
	s_barrier
; __device__ __forceinline__ unsigned cvt_pk_bf16(float lo, float hi) { unsigned r; asm volatile("v_cvt_pk_bf16_f32 %0, %1, %2" : "=v"(r) : "v"(lo), "v"(hi)); return r; }
; __device__ __forceinline__ float siluf_(float x) { return x * sigmoidf_(x); }
; #define PG8_WAIT_V(n) asm volatile("s_waitcnt vmcnt(" #n ")" ::: "memory")
; #define PG8_BAR __builtin_amdgcn_s_barrier()
;     __device__ __forceinline__ void operator()(const f32x4 (&acc)[2][2][4][2], const Unit& u, int wr, int wc, int fr, int fq) const {
;         const int row0 = u.pm * BM + wr * 64 + fr, col0 = u.pn * HALF + wc * 32 + 8 * fq;
;         float rsv[2][4]; load_rstd(rsv, ssq, row0);
; #pragma unroll
;         for (int ai = 0; ai < 2; ++ai)
; #pragma unroll
;             for (int m = 0; m < 4; ++m) { const int row = row0 + ai * HALF + m * 16; bf16_t* rowp = O + (size_t)row * ldc + col0; const float rs = rsv[ai][m];
;                 f32x4 v0, v1;
; #pragma unroll
;                 for (int j = 0; j < 4; ++j) { v0[j] = siluf_(acc[ai][0][m][0][j] * rs) * (acc[ai][1][m][0][j] * rs); v1[j] = siluf_(acc[ai][0][m][1][j] * rs) * (acc[ai][1][m][1][j] * rs); }
;                 u32x4 w; w.x = cvt_pk_bf16(v0[0], v0[1]); w.y = cvt_pk_bf16(v0[2], v0[3]); w.z = cvt_pk_bf16(v1[0], v1[1]); w.w = cvt_pk_bf16(v1[2], v1[3]);
;                 *(u32x4*)rowp = w; }
; template <class Epi, bool ALIGN_EPI>
; __device__ __forceinline__ void gemm_phase(LAS unsigned char* lds, const Gemm g, const StaticOrder& S, const Epi& E, const int tid) {
;     ...
;             PG8_WAIT_V(8); PG8_WAIT_L(0); PG8_BAR; PG8_MMA(0, 0, At, B0); PG8_MMA(0, 1, At, B1); PG8_BAR; PG8_SCHED;
;             PG8_LDA(At, 0, 1); PG8_STAGE(PG8_SB(0, 0), b2, voffB); PG8_STAGE(PG8_SB(0, 1), b2 + hB, voffB); PG8_STAGE(PG8_SA(0, 0), a2, voffA);
;             PG8_WAIT_V(8); PG8_WAIT_L(0); PG8_BAR; PG8_MMA(1, 0, At, B0); PG8_MMA(1, 1, At, B1); PG8_BAR; PG8_SCHED;
;             PG8_LDB(B0, 1, 0); PG8_LDB(B1, 1, 1); PG8_SCHED; PG8_LDA(At, 1, 0); PG8_STAGE(PG8_SA(0, 1), a2 + hA, voffA);
;             PG8_WAIT_V(8); PG8_WAIT_L(0); PG8_BAR; PG8_MMA(0, 0, At, B0); PG8_MMA(0, 1, At, B1); PG8_BAR; PG8_SCHED;
;             PG8_LDA(At, 1, 1); PG8_STAGE(PG8_SB(1, 0), b3, voffB); PG8_STAGE(PG8_SB(1, 1), b3 + hB, voffB); PG8_STAGE(PG8_SA(1, 0), a3, voffA);
;             PG8_WAIT_V(8); PG8_WAIT_L(0); PG8_BAR; PG8_MMA(1, 0, At, B0); PG8_MMA(1, 1, At, B1); PG8_BAR; PG8_SCHED;
	s_add_i32 s10, s10, s45
	v_lshl_add_u64 v[166:167], v[226:227], 0, s[92:93]
	s_mov_b32 m0, s10
	ds_read_b128 v[192:195], v153 offset:49152
	ds_read_b128 v[196:199], v153 offset:50176
	ds_read_b128 v[200:203], v153 offset:51200
	ds_read_b128 v[204:207], v153 offset:52224
	ds_read_b128 v[208:211], v153 offset:53248
	ds_read_b128 v[212:215], v153 offset:54272
	ds_read_b128 v[216:219], v153 offset:55296
	ds_read_b128 v[240:243], v153 offset:56320
	global_load_lds_dwordx4 v[166:167], off
	v_lshl_add_u64 v[166:167], v[244:245], 0, s[92:93]
	s_add_i32 m0, s10, 0x2000
	s_add_i32 s10, s65, s45
	global_load_lds_dwordx4 v[166:167], off
	v_lshl_add_u64 v[166:167], v[246:247], 0, s[92:93]
	s_mov_b32 m0, s10
	s_nop 0
	global_load_lds_dwordx4 v[166:167], off
	v_lshl_add_u64 v[166:167], v[220:221], 0, s[92:93]
	s_add_i32 m0, s10, 0x2000
	s_nop 0
	global_load_lds_dwordx4 v[166:167], off
	v_lshl_add_u64 v[166:167], v[248:249], 0, s[92:93]
	s_mov_b32 m0, s56
	s_nop 0
	global_load_lds_dwordx4 v[166:167], off
	v_lshl_add_u64 v[166:167], v[250:251], 0, s[92:93]
	s_mov_b32 m0, s57
	s_nop 0
	global_load_lds_dwordx4 v[166:167], off
	s_waitcnt vmcnt(8)
	s_waitcnt lgkmcnt(0)
	s_barrier
	s_setprio 1
	s_waitcnt lgkmcnt(0)
	v_mfma_f32_16x16x32_bf16 v[56:59], v[146:149], v[192:195], v[56:59]
	v_mfma_f32_16x16x32_bf16 v[48:51], v[158:161], v[192:195], v[48:51]
	v_mfma_f32_16x16x32_bf16 v[40:43], v[146:149], v[200:203], v[40:43]
	v_mfma_f32_16x16x32_bf16 v[32:35], v[158:161], v[200:203], v[32:35]
	v_mfma_f32_16x16x32_bf16 v[24:27], v[146:149], v[208:211], v[24:27]
	v_mfma_f32_16x16x32_bf16 v[16:19], v[158:161], v[208:211], v[16:19]
	v_mfma_f32_16x16x32_bf16 v[8:11], v[146:149], v[216:219], v[8:11]
	v_mfma_f32_16x16x32_bf16 v[4:7], v[158:161], v[216:219], v[4:7]
	v_mfma_f32_16x16x32_bf16 v[56:59], v[154:157], v[196:199], v[56:59]
	v_lshrrev_b32_e32 v171, 8, v170
	v_and_b32_e32 v234, 15, v170
	v_lshl_add_u32 v171, v171, 6, v234
	s_lshl_b32 s98, s64, 8
	v_add_u32_e32 v171, s98, v171
	v_mul_lo_u32 v171, v171, s28
	v_bfe_u32 v234, v170, 6, 2
	v_bfe_u32 v224, v170, 4, 2
	v_lshlrev_b32_e32 v234, 5, v234
	v_lshl_or_b32 v234, v224, 3, v234
	s_lshl_b32 s98, s63, 7
	v_add_u32_e32 v234, s98, v234
	v_add_lshl_u32 v232, v171, v234, 1
	v_mfma_f32_16x16x32_bf16 v[48:51], v[162:165], v[196:199], v[48:51]
	v_mov_b32_e32 v233, 0
	v_lshl_add_u64 v[232:233], v[232:233], 0, s[30:31]
	s_lshl_b32 s98, s28, 5
	s_mov_b32 s99, 0
	s_mov_b32 s100, 0xbfb8aa3b
	s_mov_b32 s101, 0xbfb8aa3b
	v_mul_f32_e32 v120, v172, v120
	v_mul_f32_e32 v121, v172, v121
	v_mul_f32_e32 v122, v172, v122
	v_mul_f32_e32 v123, v172, v123
	v_mul_f32_e32 v124, v172, v124
	v_mul_f32_e32 v125, v172, v125
	v_mul_f32_e32 v126, v172, v126
	v_mfma_f32_16x16x32_bf16 v[40:43], v[154:157], v[204:207], v[40:43]
	v_mul_f32_e32 v127, v172, v127
	v_mul_f32_e32 v224, s100, v120
	v_mul_f32_e32 v225, s101, v121
	v_mul_f32_e32 v228, s100, v122
	v_mul_f32_e32 v229, s101, v123
	v_exp_f32_e32 v224, v224
	v_exp_f32_e32 v225, v225
	v_exp_f32_e32 v228, v228
	v_exp_f32_e32 v229, v229
	v_add_f32_e32 v224, 1.0, v224
	v_add_f32_e32 v225, 1.0, v225
	v_add_f32_e32 v228, 1.0, v228
	v_add_f32_e32 v229, 1.0, v229
	v_mfma_f32_16x16x32_bf16 v[32:35], v[162:165], v[204:207], v[32:35]
	v_rcp_f32_e32 v224, v224
	v_rcp_f32_e32 v225, v225
	v_rcp_f32_e32 v228, v228
	v_rcp_f32_e32 v229, v229
	v_nop
	v_mul_f32_e32 v120, v224, v120
	v_mul_f32_e32 v121, v225, v121
	v_mul_f32_e32 v122, v228, v122
	v_mul_f32_e32 v123, v229, v123
	v_mul_f32_e32 v120, v124, v120
	v_mul_f32_e32 v121, v125, v121
	v_mul_f32_e32 v122, v126, v122
	v_mul_f32_e32 v123, v127, v123
	v_mfma_f32_16x16x32_bf16 v[24:27], v[154:157], v[212:215], v[24:27]
	v_mul_f32_e32 v112, v172, v112
	v_mul_f32_e32 v113, v172, v113
	v_mul_f32_e32 v114, v172, v114
	v_mul_f32_e32 v115, v172, v115
	v_mul_f32_e32 v116, v172, v116
	v_mul_f32_e32 v117, v172, v117
	v_mul_f32_e32 v118, v172, v118
	v_mul_f32_e32 v119, v172, v119
	v_mul_f32_e32 v224, s100, v112
	v_mul_f32_e32 v225, s101, v113
	v_mul_f32_e32 v228, s100, v114
	v_mul_f32_e32 v229, s101, v115
	v_exp_f32_e32 v224, v224
	v_mfma_f32_16x16x32_bf16 v[16:19], v[162:165], v[212:215], v[16:19]
	v_exp_f32_e32 v225, v225
	v_exp_f32_e32 v228, v228
	v_exp_f32_e32 v229, v229
	v_add_f32_e32 v224, 1.0, v224
	v_add_f32_e32 v225, 1.0, v225
	v_add_f32_e32 v228, 1.0, v228
	v_add_f32_e32 v229, 1.0, v229
	v_rcp_f32_e32 v224, v224
	v_rcp_f32_e32 v225, v225
	v_rcp_f32_e32 v228, v228
	v_rcp_f32_e32 v229, v229
	v_nop
	v_mul_f32_e32 v112, v224, v112
	v_mfma_f32_16x16x32_bf16 v[8:11], v[154:157], v[240:243], v[8:11]
	v_mul_f32_e32 v113, v225, v113
	v_mul_f32_e32 v114, v228, v114
	v_mul_f32_e32 v115, v229, v115
	v_mul_f32_e32 v112, v116, v112
	v_mul_f32_e32 v113, v117, v113
	v_mul_f32_e32 v114, v118, v114
	v_mul_f32_e32 v115, v119, v115
	v_cvt_pk_bf16_f32 v120, v120, v121
	v_cvt_pk_bf16_f32 v121, v122, v123
	v_cvt_pk_bf16_f32 v122, v112, v113
	v_cvt_pk_bf16_f32 v123, v114, v115
	global_store_dwordx4 v[232:233], v[120:123], off
	v_lshl_add_u64 v[232:233], v[232:233], 0, s[98:99]
	v_mfma_f32_16x16x32_bf16 v[4:7], v[162:165], v[240:243], v[4:7]
	v_mul_f32_e32 v104, v173, v104
	v_mul_f32_e32 v105, v173, v105
	v_mul_f32_e32 v106, v173, v106
	v_mul_f32_e32 v107, v173, v107
	v_mul_f32_e32 v108, v173, v108
	v_mul_f32_e32 v109, v173, v109
	v_mul_f32_e32 v110, v173, v110
	v_mul_f32_e32 v111, v173, v111
	v_mul_f32_e32 v224, s100, v104
	v_mul_f32_e32 v225, s101, v105
	v_mul_f32_e32 v228, s100, v106
	v_mul_f32_e32 v229, s101, v107
	v_exp_f32_e32 v224, v224
	s_setprio 0
	s_setprio 1
	v_mfma_f32_16x16x32_bf16 v[60:63], v[176:179], v[192:195], v[60:63]
	v_exp_f32_e32 v225, v225
	v_exp_f32_e32 v228, v228
; __device__ __forceinline__ unsigned cvt_pk_bf16(float lo, float hi) { unsigned r; asm volatile("v_cvt_pk_bf16_f32 %0, %1, %2" : "=v"(r) : "v"(lo), "v"(hi)); return r; }
; __device__ __forceinline__ float siluf_(float x) { return x * sigmoidf_(x); }
; #define PG8_MMA(ai, bj, At, Bt) do { __builtin_amdgcn_s_setprio(1); _Pragma("unroll") for (int k = 0; k < 2; ++k) _Pragma("unroll") for (int m = 0; m < 4; ++m) _Pragma("unroll") for (int n = 0; n < 2; ++n) \
;         acc[ai][bj][m][n] = __builtin_amdgcn_mfma_f32_16x16x32_bf16(Bt[n][k], At[m][k], acc[ai][bj][m][n], 0, 0, 0); __builtin_amdgcn_s_setprio(0); } while (0)
; #define PG8_WAIT_V(n) asm volatile("s_waitcnt vmcnt(" #n ")" ::: "memory")
; #define PG8_WAIT_L(n) asm volatile("s_waitcnt lgkmcnt(" #n ")" ::: "memory")
; #define PG8_BAR __builtin_amdgcn_s_barrier()
; #define PG8_SCHED __builtin_amdgcn_sched_barrier(0)
;     __device__ __forceinline__ void operator()(const f32x4 (&acc)[2][2][4][2], const Unit& u, int wr, int wc, int fr, int fq) const {
;     ...
;             for (int m = 0; m < 4; ++m) { const int row = row0 + ai * HALF + m * 16; bf16_t* rowp = O + (size_t)row * ldc + col0; const float rs = rsv[ai][m];
;                 f32x4 v0, v1;
; #pragma unroll
;                 for (int j = 0; j < 4; ++j) { v0[j] = siluf_(acc[ai][0][m][0][j] * rs) * (acc[ai][1][m][0][j] * rs); v1[j] = siluf_(acc[ai][0][m][1][j] * rs) * (acc[ai][1][m][1][j] * rs); }
;                 u32x4 w; w.x = cvt_pk_bf16(v0[0], v0[1]); w.y = cvt_pk_bf16(v0[2], v0[3]); w.z = cvt_pk_bf16(v1[0], v1[1]); w.w = cvt_pk_bf16(v1[2], v1[3]);
;                 *(u32x4*)rowp = w; }
; template <class Epi, bool ALIGN_EPI>
; __device__ __forceinline__ void gemm_phase(LAS unsigned char* lds, const Gemm g, const StaticOrder& S, const Epi& E, const int tid) {
;     ...
;             PG8_WAIT_V(8); PG8_WAIT_L(0); PG8_BAR; PG8_MMA(1, 0, At, B0); PG8_MMA(1, 1, At, B1); PG8_BAR; PG8_SCHED;
	v_exp_f32_e32 v229, v229
	v_add_f32_e32 v224, 1.0, v224
	v_add_f32_e32 v225, 1.0, v225
	v_add_f32_e32 v228, 1.0, v228
	v_add_f32_e32 v229, 1.0, v229
	v_rcp_f32_e32 v224, v224
	v_rcp_f32_e32 v225, v225
	v_rcp_f32_e32 v228, v228
	v_rcp_f32_e32 v229, v229
	v_nop
	v_mul_f32_e32 v104, v224, v104
	v_mfma_f32_16x16x32_bf16 v[52:55], v[184:187], v[192:195], v[52:55]
	v_mul_f32_e32 v105, v225, v105
	v_mul_f32_e32 v106, v228, v106
	v_mul_f32_e32 v107, v229, v107
	v_mul_f32_e32 v104, v108, v104
	v_mul_f32_e32 v105, v109, v105
	v_mul_f32_e32 v106, v110, v106
	v_mul_f32_e32 v107, v111, v107
	v_mul_f32_e32 v96, v173, v96
	v_mul_f32_e32 v97, v173, v97
	v_mul_f32_e32 v98, v173, v98
	v_mul_f32_e32 v99, v173, v99
	v_mul_f32_e32 v100, v173, v100
	v_mul_f32_e32 v101, v173, v101
	v_mfma_f32_16x16x32_bf16 v[44:47], v[176:179], v[200:203], v[44:47]
	v_mul_f32_e32 v102, v173, v102
	v_mul_f32_e32 v103, v173, v103
	v_mul_f32_e32 v224, s100, v96
	v_mul_f32_e32 v225, s101, v97
	v_mul_f32_e32 v228, s100, v98
	v_mul_f32_e32 v229, s101, v99
	v_exp_f32_e32 v224, v224
	v_exp_f32_e32 v225, v225
	v_exp_f32_e32 v228, v228
	v_exp_f32_e32 v229, v229
	v_add_f32_e32 v224, 1.0, v224
	v_add_f32_e32 v225, 1.0, v225
	v_add_f32_e32 v228, 1.0, v228
	v_mfma_f32_16x16x32_bf16 v[36:39], v[184:187], v[200:203], v[36:39]
	v_add_f32_e32 v229, 1.0, v229
	v_rcp_f32_e32 v224, v224
	v_rcp_f32_e32 v225, v225
	v_rcp_f32_e32 v228, v228
	v_rcp_f32_e32 v229, v229
	v_nop
	v_mul_f32_e32 v96, v224, v96
	v_mul_f32_e32 v97, v225, v97
	v_mul_f32_e32 v98, v228, v98
	v_mul_f32_e32 v99, v229, v99
	v_mul_f32_e32 v96, v100, v96
	v_mul_f32_e32 v97, v101, v97
	v_mul_f32_e32 v98, v102, v98
	v_mfma_f32_16x16x32_bf16 v[28:31], v[176:179], v[208:211], v[28:31]
	v_mul_f32_e32 v99, v103, v99
	v_cvt_pk_bf16_f32 v104, v104, v105
	v_cvt_pk_bf16_f32 v105, v106, v107
	v_cvt_pk_bf16_f32 v106, v96, v97
	v_cvt_pk_bf16_f32 v107, v98, v99
	global_store_dwordx4 v[232:233], v[104:107], off
	v_lshl_add_u64 v[232:233], v[232:233], 0, s[98:99]
	v_mul_f32_e32 v88, v236, v88
	v_mul_f32_e32 v89, v236, v89
	v_mul_f32_e32 v90, v236, v90
	v_mul_f32_e32 v91, v236, v91
	v_mul_f32_e32 v92, v236, v92
	v_mul_f32_e32 v93, v236, v93
	v_mfma_f32_16x16x32_bf16 v[20:23], v[184:187], v[208:211], v[20:23]
	v_mul_f32_e32 v94, v236, v94
	v_mul_f32_e32 v95, v236, v95
	v_mul_f32_e32 v224, s100, v88
	v_mul_f32_e32 v225, s101, v89
	v_mul_f32_e32 v228, s100, v90
	v_mul_f32_e32 v229, s101, v91
	v_exp_f32_e32 v224, v224
	v_exp_f32_e32 v225, v225
	v_exp_f32_e32 v228, v228
	v_exp_f32_e32 v229, v229
	v_add_f32_e32 v224, 1.0, v224
	v_add_f32_e32 v225, 1.0, v225
	v_add_f32_e32 v228, 1.0, v228
	v_mfma_f32_16x16x32_bf16 v[12:15], v[176:179], v[216:219], v[12:15]
	v_add_f32_e32 v229, 1.0, v229
	v_rcp_f32_e32 v224, v224
	v_rcp_f32_e32 v225, v225
	v_rcp_f32_e32 v228, v228
	v_rcp_f32_e32 v229, v229
	v_nop
	v_mul_f32_e32 v88, v224, v88
	v_mul_f32_e32 v89, v225, v89
	v_mul_f32_e32 v90, v228, v90
	v_mul_f32_e32 v91, v229, v91
	v_mul_f32_e32 v88, v92, v88
	v_mul_f32_e32 v89, v93, v89
	v_mul_f32_e32 v90, v94, v90
	v_mfma_f32_16x16x32_bf16 v[0:3], v[184:187], v[216:219], v[0:3]
	v_mul_f32_e32 v91, v95, v91
	v_mul_f32_e32 v80, v236, v80
	v_mul_f32_e32 v81, v236, v81
	v_mul_f32_e32 v82, v236, v82
	v_mul_f32_e32 v83, v236, v83
	v_mul_f32_e32 v84, v236, v84
	v_mul_f32_e32 v85, v236, v85
	v_mul_f32_e32 v86, v236, v86
	v_mul_f32_e32 v87, v236, v87
	v_mul_f32_e32 v224, s100, v80
	v_mul_f32_e32 v225, s101, v81
	v_mul_f32_e32 v228, s100, v82
	v_mul_f32_e32 v229, s101, v83
	v_mfma_f32_16x16x32_bf16 v[60:63], v[180:183], v[196:199], v[60:63]
	v_exp_f32_e32 v224, v224
	v_exp_f32_e32 v225, v225
	v_exp_f32_e32 v228, v228
	v_exp_f32_e32 v229, v229
	v_add_f32_e32 v224, 1.0, v224
	v_add_f32_e32 v225, 1.0, v225
	v_add_f32_e32 v228, 1.0, v228
	v_add_f32_e32 v229, 1.0, v229
; __device__ __forceinline__ float siluf_(float x) { return x * sigmoidf_(x); }
; #define PG8_BAR __builtin_amdgcn_s_barrier()
;     __device__ __forceinline__ void operator()(const f32x4 (&acc)[2][2][4][2], const Unit& u, int wr, int wc, int fr, int fq) const {
;     ...
;             for (int m = 0; m < 4; ++m) { const int row = row0 + ai * HALF + m * 16; bf16_t* rowp = O + (size_t)row * ldc + col0; const float rs = rsv[ai][m];
;                 f32x4 v0, v1;
; #pragma unroll
;                 for (int j = 0; j < 4; ++j) { v0[j] = siluf_(acc[ai][0][m][0][j] * rs) * (acc[ai][1][m][0][j] * rs); v1[j] = siluf_(acc[ai][0][m][1][j] * rs) * (acc[ai][1][m][1][j] * rs); }
;                 u32x4 w; w.x = cvt_pk_bf16(v0[0], v0[1]); w.y = cvt_pk_bf16(v0[2], v0[3]); w.z = cvt_pk_bf16(v1[0], v1[1]); w.w = cvt_pk_bf16(v1[2], v1[3]);
;                 *(u32x4*)rowp = w; }
; template <class Epi, bool ALIGN_EPI>
; __device__ __forceinline__ void gemm_phase(LAS unsigned char* lds, const Gemm g, const StaticOrder& S, const Epi& E, const int tid) {
;     ...
;     for (;;) {
;         const bool has_next = S.next(ui + 1, nxt);
;         const char* nA = has_next ? (const char*)g.A + (size_t)nxt.pm * tA + (size_t)nxt.pn * g.apn * 2 : cA; const char* nB = has_next ? (const char*)g.Bt + (size_t)nxt.pn * tB : cB;
;         for (int t = 0; t < nt; t += 2) {
;             const bool last = (t == nt - 2);
;             const char* a1 = cA + (size_t)(t + 1) * kstep;
;             const char* a2 = last ? nA : cA + (size_t)(t + 2) * kstep; const char* b2 = last ? nB : cB + (size_t)(t + 2) * kstep;
;             const char* a3 = a2 + kstep; const char* b3 = b2 + kstep;
;             PG8_LDB(B0, 0, 0); PG8_LDB(B1, 0, 1); PG8_SCHED; PG8_LDA(At, 0, 0); PG8_STAGE(PG8_SA(1, 1), a1 + hA, voffA);
;             PG8_WAIT_V(8); PG8_WAIT_L(0); PG8_BAR; PG8_MMA(0, 0, At, B0); PG8_MMA(0, 1, At, B1); PG8_BAR; PG8_SCHED;
;             PG8_LDA(At, 0, 1); PG8_STAGE(PG8_SB(0, 0), b2, voffB); PG8_STAGE(PG8_SB(0, 1), b2 + hB, voffB); PG8_STAGE(PG8_SA(0, 0), a2, voffA);
;             PG8_WAIT_V(8); PG8_WAIT_L(0); PG8_BAR; PG8_MMA(1, 0, At, B0); PG8_MMA(1, 1, At, B1); PG8_BAR; PG8_SCHED;
;             PG8_LDB(B0, 1, 0); PG8_LDB(B1, 1, 1); PG8_SCHED; PG8_LDA(At, 1, 0); PG8_STAGE(PG8_SA(0, 1), a2 + hA, voffA);
;             PG8_WAIT_V(8); PG8_WAIT_L(0); PG8_BAR; PG8_MMA(0, 0, At, B0); PG8_MMA(0, 1, At, B1); PG8_BAR; PG8_SCHED;
	v_rcp_f32_e32 v224, v224
	v_rcp_f32_e32 v225, v225
	v_rcp_f32_e32 v228, v228
	v_rcp_f32_e32 v229, v229
	v_nop
	v_mfma_f32_16x16x32_bf16 v[52:55], v[188:191], v[196:199], v[52:55]
	v_mul_f32_e32 v80, v224, v80
	v_mul_f32_e32 v81, v225, v81
	v_mul_f32_e32 v82, v228, v82
	v_mul_f32_e32 v83, v229, v83
	v_mul_f32_e32 v80, v84, v80
	v_mul_f32_e32 v81, v85, v81
	v_mul_f32_e32 v82, v86, v82
	v_mul_f32_e32 v83, v87, v83
	v_cvt_pk_bf16_f32 v88, v88, v89
	v_cvt_pk_bf16_f32 v89, v90, v91
	v_cvt_pk_bf16_f32 v90, v80, v81
	v_cvt_pk_bf16_f32 v91, v82, v83
	global_store_dwordx4 v[232:233], v[88:91], off
	v_mfma_f32_16x16x32_bf16 v[44:47], v[180:183], v[204:207], v[44:47]
	v_lshl_add_u64 v[232:233], v[232:233], 0, s[98:99]
	v_mul_f32_e32 v72, v237, v72
	v_mul_f32_e32 v73, v237, v73
	v_mul_f32_e32 v74, v237, v74
	v_mul_f32_e32 v75, v237, v75
	v_mul_f32_e32 v76, v237, v76
	v_mul_f32_e32 v77, v237, v77
	v_mul_f32_e32 v78, v237, v78
	v_mul_f32_e32 v79, v237, v79
	v_mul_f32_e32 v224, s100, v72
	v_mul_f32_e32 v225, s101, v73
	v_mul_f32_e32 v228, s100, v74
	v_mul_f32_e32 v229, s101, v75
	v_mfma_f32_16x16x32_bf16 v[36:39], v[188:191], v[204:207], v[36:39]
	v_exp_f32_e32 v224, v224
	v_exp_f32_e32 v225, v225
	v_exp_f32_e32 v228, v228
	v_exp_f32_e32 v229, v229
	v_add_f32_e32 v224, 1.0, v224
	v_add_f32_e32 v225, 1.0, v225
	v_add_f32_e32 v228, 1.0, v228
	v_add_f32_e32 v229, 1.0, v229
	v_rcp_f32_e32 v224, v224
	v_rcp_f32_e32 v225, v225
	v_rcp_f32_e32 v228, v228
	v_rcp_f32_e32 v229, v229
	v_nop
	v_mfma_f32_16x16x32_bf16 v[28:31], v[180:183], v[212:215], v[28:31]
	v_mul_f32_e32 v72, v224, v72
	v_mul_f32_e32 v73, v225, v73
	v_mul_f32_e32 v74, v228, v74
	v_mul_f32_e32 v75, v229, v75
	v_mul_f32_e32 v72, v76, v72
	v_mul_f32_e32 v73, v77, v73
	v_mul_f32_e32 v74, v78, v74
	v_mul_f32_e32 v75, v79, v75
	v_mul_f32_e32 v64, v237, v64
	v_mul_f32_e32 v65, v237, v65
	v_mul_f32_e32 v66, v237, v66
	v_mul_f32_e32 v67, v237, v67
	v_mul_f32_e32 v68, v237, v68
	v_mfma_f32_16x16x32_bf16 v[20:23], v[188:191], v[212:215], v[20:23]
	v_mul_f32_e32 v69, v237, v69
	v_mul_f32_e32 v70, v237, v70
	v_mul_f32_e32 v71, v237, v71
	v_mul_f32_e32 v224, s100, v64
	v_mul_f32_e32 v225, s101, v65
	v_mul_f32_e32 v228, s100, v66
	v_mul_f32_e32 v229, s101, v67
	v_exp_f32_e32 v224, v224
	v_exp_f32_e32 v225, v225
	v_exp_f32_e32 v228, v228
	v_exp_f32_e32 v229, v229
	v_add_f32_e32 v224, 1.0, v224
	v_add_f32_e32 v225, 1.0, v225
	v_mfma_f32_16x16x32_bf16 v[12:15], v[180:183], v[240:243], v[12:15]
	v_add_f32_e32 v228, 1.0, v228
	v_add_f32_e32 v229, 1.0, v229
	v_rcp_f32_e32 v224, v224
	v_rcp_f32_e32 v225, v225
	v_rcp_f32_e32 v228, v228
	v_rcp_f32_e32 v229, v229
	v_nop
	v_mul_f32_e32 v64, v224, v64
	v_mul_f32_e32 v65, v225, v65
	v_mul_f32_e32 v66, v228, v66
	v_mul_f32_e32 v67, v229, v67
	v_mul_f32_e32 v64, v68, v64
	v_mul_f32_e32 v65, v69, v65
	v_mfma_f32_16x16x32_bf16 v[0:3], v[188:191], v[240:243], v[0:3]
	v_mul_f32_e32 v66, v70, v66
	v_mul_f32_e32 v67, v71, v67
	v_cvt_pk_bf16_f32 v72, v72, v73
	v_cvt_pk_bf16_f32 v73, v74, v75
	v_cvt_pk_bf16_f32 v74, v64, v65
	v_cvt_pk_bf16_f32 v75, v66, v67
	global_store_dwordx4 v[232:233], v[72:75], off
	v_lshl_add_u64 v[232:233], v[232:233], 0, s[98:99]
	v_lshl_add_u64 v[232:233], v[232:233], 0, s[98:99]
	v_lshl_add_u64 v[232:233], v[232:233], 0, s[98:99]
	v_lshl_add_u64 v[232:233], v[232:233], 0, s[98:99]
	v_lshl_add_u64 v[232:233], v[232:233], 0, s[98:99]
	s_setprio 0
	s_barrier
	v_lshl_add_u64 v[142:143], v[142:143], 0, s[80:81]
	v_lshl_add_u64 v[144:145], v[144:145], 0, s[80:81]
	s_and_b64 vcc, exec, s[8:9]
	s_cbranch_vccnz .Lgu_notdefer
	s_cmp_lg_u32 s62, s64
	s_cbranch_scc1 .Lgu_notdefer
	s_mov_b32 s101, 1
	s_mov_b32 s63, s61
	s_mov_b32 s64, s62
	v_mov_b64_e32 v[144:145], v[140:141]
	v_mov_b64_e32 v[142:143], v[138:139]
	s_branch .LBB0_300

; __device__ __forceinline__ unsigned cvt_pk_bf16(float lo, float hi) { unsigned r; asm volatile("v_cvt_pk_bf16_f32 %0, %1, %2" : "=v"(r) : "v"(lo), "v"(hi)); return r; }
; __device__ __forceinline__ float gelu_tanh(float x) { const float u = 0.7978845608028654f * (x + 0.044715f * x * x * x); return x * fast_rcp(1.0f + fast_exp2(-2.0f * LOG2E * u)); }
; #define PG8_STAGE(bufoff, gbase, voff) do { _Pragma("unroll") for (int _i = 0; _i < 2; ++_i) \
;         __builtin_amdgcn_global_load_lds((const unsigned*)((const char*)(gbase) + (voff)[_i]), (LAS unsigned*)(lds + (bufoff) + ldsw + _i * 8192), 16, 0, 0); } while (0)
; #define PG8_LDA(dst, b, h) do { _Pragma("unroll") for (int m = 0; m < 4; ++m) _Pragma("unroll") for (int k = 0; k < 2; ++k) dst[m][k] = *(const LAS bf16x8*)(lds + PG8_SA(b, h) + aoff + m * 2048 + k * 1024); } while (0)
; #define PG8_LDB(dst, b, h) do { _Pragma("unroll") for (int n = 0; n < 2; ++n) _Pragma("unroll") for (int k = 0; k < 2; ++k) dst[n][k] = *(const LAS bf16x8*)(lds + PG8_SB(b, h) + boff + n * 2048 + k * 1024); } while (0)
; #define PG8_WAIT_V(n) asm volatile("s_waitcnt vmcnt(" #n ")" ::: "memory")
;     __device__ __forceinline__ void operator()(const f32x4 (&acc)[2][2][4][2], const Unit& u, int wr, int wc, int fr, int fq) const {
;     ...
;             for (int m = 0; m < 4; ++m) { const int row = row0 + ai * HALF + m * 16; bf16_t* rowp = O + (size_t)row * ldc + col0; const float rs = rsv[ai][m];
; #pragma unroll
;                 for (int bj = 0; bj < 2; ++bj) { f32x4 v0 = acc[ai][bj][m][0] * rs, v1 = acc[ai][bj][m][1] * rs;
;                     if (ACT == 1) {
; #pragma unroll
;                         for (int j = 0; j < 4; ++j) { v0[j] = gelu_tanh(v0[j]); v1[j] = gelu_tanh(v1[j]); } }
;                     u32x4 w; w.x = cvt_pk_bf16(v0[0], v0[1]); w.y = cvt_pk_bf16(v0[2], v0[3]); w.z = cvt_pk_bf16(v1[0], v1[1]); w.w = cvt_pk_bf16(v1[2], v1[3]);
;                     *(u32x4*)(rowp + bj * HALF) = w; } }
; template <class Epi, bool ALIGN_EPI>
; __device__ __forceinline__ void gemm_phase(LAS unsigned char* lds, const Gemm g, const StaticOrder& S, const Epi& E, const int tid) {
;     ...
;             PG8_LDB(B0, 0, 0); PG8_LDB(B1, 0, 1); PG8_SCHED; PG8_LDA(At, 0, 0); PG8_STAGE(PG8_SA(1, 1), a1 + hA, voffA);
;             PG8_WAIT_V(8); PG8_WAIT_L(0); PG8_BAR; PG8_MMA(0, 0, At, B0); PG8_MMA(0, 1, At, B1); PG8_BAR; PG8_SCHED;
.Lq5_first_epi:
	s_add_i32 s11, s10, 2
	s_cmp_eq_u32 s55, s10
	s_cselect_b64 vcc, -1, 0
	v_add_u32_e32 v148, s33, v149
	s_add_i32 s10, 0, 0x14000
	ds_read_b128 v[152:155], v148
	ds_read_b128 v[156:159], v148 offset:1024
	ds_read_b128 v[160:163], v148 offset:2048
	ds_read_b128 v[164:167], v148 offset:3072
	v_add_u32_e32 v148, s10, v149
	ds_read_b128 v[176:179], v148
	ds_read_b128 v[180:183], v148 offset:1024
	ds_read_b128 v[184:187], v148 offset:2048
	ds_read_b128 v[188:191], v148 offset:3072
	v_lshl_add_u64 v[146:147], v[142:143], 0, s[92:93]
	v_cndmask_b32_e32 v147, v147, v139, vcc
	v_cndmask_b32_e32 v146, v146, v138, vcc
	v_cndmask_b32_e32 v221, v145, v141, vcc
	v_cndmask_b32_e32 v220, v144, v140, vcc
	v_lshl_add_u64 v[244:245], v[142:143], 0, v[134:135]
	s_add_i32 m0, s25, 0xc000
	ds_read_b128 v[192:195], v151
	ds_read_b128 v[196:199], v151 offset:1024
	ds_read_b128 v[200:203], v151 offset:2048
	ds_read_b128 v[204:207], v151 offset:3072
	ds_read_b128 v[208:211], v151 offset:4096
	ds_read_b128 v[212:215], v151 offset:5120
	ds_read_b128 v[216:219], v151 offset:6144
	ds_read_b128 v[240:243], v151 offset:7168
	global_load_lds_dwordx4 v[244:245], off
	v_lshl_add_u64 v[244:245], v[142:143], 0, v[136:137]
	s_add_i32 m0, s25, 0xe000
	s_nop 0
	global_load_lds_dwordx4 v[244:245], off
	s_waitcnt vmcnt(16)
	s_waitcnt lgkmcnt(0)
	s_barrier
	s_setprio 1
	s_waitcnt lgkmcnt(0)
	v_mfma_f32_16x16x32_bf16 v[124:127], v[152:155], v[192:195], 0
	v_mfma_f32_16x16x32_bf16 v[120:123], v[160:163], v[192:195], 0
	v_mfma_f32_16x16x32_bf16 v[108:111], v[152:155], v[200:203], 0
	v_mfma_f32_16x16x32_bf16 v[104:107], v[160:163], v[200:203], 0
	v_mfma_f32_16x16x32_bf16 v[92:95], v[152:155], v[208:211], 0
	v_mfma_f32_16x16x32_bf16 v[88:91], v[160:163], v[208:211], 0
	v_mfma_f32_16x16x32_bf16 v[76:79], v[152:155], v[216:219], 0
	v_mfma_f32_16x16x32_bf16 v[72:75], v[160:163], v[216:219], 0
	v_mfma_f32_16x16x32_bf16 v[124:127], v[156:159], v[196:199], v[124:127]
	s_lshl_b32 s98, s28, 5
	s_mov_b32 s99, 0
	v_mul_f32_e32 v60, v238, v60
	v_mul_f32_e32 v61, v238, v61
	v_mul_f32_e32 v62, v238, v62
	v_mfma_f32_16x16x32_bf16 v[120:123], v[164:167], v[196:199], v[120:123]
	v_mul_f32_e32 v63, v238, v63
	v_mul_f32_e32 v56, v238, v56
	v_mul_f32_e32 v57, v238, v57
	v_mul_f32_e32 v58, v238, v58
	v_mul_f32_e32 v59, v238, v59
	v_mfma_f32_16x16x32_bf16 v[108:111], v[156:159], v[204:207], v[108:111]
	v_cvt_pk_bf16_f32 v60, v60, v61
	v_cvt_pk_bf16_f32 v61, v62, v63
	v_cvt_pk_bf16_f32 v62, v56, v57
	v_cvt_pk_bf16_f32 v63, v58, v59
	global_store_dwordx4 v[232:233], v[60:63], off
	v_mfma_f32_16x16x32_bf16 v[104:107], v[164:167], v[204:207], v[104:107]
	v_mul_f32_e32 v52, v238, v52
	v_mul_f32_e32 v53, v238, v53
	v_mul_f32_e32 v54, v238, v54
	v_mul_f32_e32 v55, v238, v55
	v_mul_f32_e32 v48, v238, v48
	v_mfma_f32_16x16x32_bf16 v[92:95], v[156:159], v[212:215], v[92:95]
	v_mul_f32_e32 v49, v238, v49
	v_mul_f32_e32 v50, v238, v50
	v_mul_f32_e32 v51, v238, v51
	v_cvt_pk_bf16_f32 v52, v52, v53
	v_cvt_pk_bf16_f32 v53, v54, v55
	v_mfma_f32_16x16x32_bf16 v[88:91], v[164:167], v[212:215], v[88:91]
	v_cvt_pk_bf16_f32 v54, v48, v49
	v_cvt_pk_bf16_f32 v55, v50, v51
	global_store_dwordx4 v[232:233], v[52:55], off offset:256
	v_lshl_add_u64 v[232:233], v[232:233], 0, s[98:99]
	v_mul_f32_e32 v44, v239, v44
	v_mfma_f32_16x16x32_bf16 v[76:79], v[156:159], v[240:243], v[76:79]
	v_mul_f32_e32 v45, v239, v45
	v_mul_f32_e32 v46, v239, v46
	v_mul_f32_e32 v47, v239, v47
	v_mul_f32_e32 v40, v239, v40
	v_mul_f32_e32 v41, v239, v41
	v_mfma_f32_16x16x32_bf16 v[72:75], v[164:167], v[240:243], v[72:75]
	v_mul_f32_e32 v42, v239, v42
	v_mul_f32_e32 v43, v239, v43
	v_cvt_pk_bf16_f32 v44, v44, v45
	v_cvt_pk_bf16_f32 v45, v46, v47
	v_cvt_pk_bf16_f32 v46, v40, v41
	s_setprio 0
	s_setprio 1
	v_mfma_f32_16x16x32_bf16 v[116:119], v[176:179], v[192:195], 0
	v_cvt_pk_bf16_f32 v47, v42, v43
	global_store_dwordx4 v[232:233], v[44:47], off
	v_mul_f32_e32 v36, v239, v36
	v_mul_f32_e32 v37, v239, v37
	v_mul_f32_e32 v38, v239, v38
	v_mfma_f32_16x16x32_bf16 v[112:115], v[184:187], v[192:195], 0
	v_mul_f32_e32 v39, v239, v39
	v_mul_f32_e32 v32, v239, v32
	v_mul_f32_e32 v33, v239, v33
	v_mul_f32_e32 v34, v239, v34
	v_mul_f32_e32 v35, v239, v35
	v_mfma_f32_16x16x32_bf16 v[100:103], v[176:179], v[200:203], 0
	v_cvt_pk_bf16_f32 v36, v36, v37
	v_cvt_pk_bf16_f32 v37, v38, v39
	v_cvt_pk_bf16_f32 v38, v32, v33
	v_cvt_pk_bf16_f32 v39, v34, v35
	global_store_dwordx4 v[232:233], v[36:39], off offset:256
	v_mfma_f32_16x16x32_bf16 v[96:99], v[184:187], v[200:203], 0
	v_lshl_add_u64 v[232:233], v[232:233], 0, s[98:99]
	v_mul_f32_e32 v28, v230, v28
	v_mul_f32_e32 v29, v230, v29
	v_mul_f32_e32 v30, v230, v30
	v_mul_f32_e32 v31, v230, v31
	v_mfma_f32_16x16x32_bf16 v[84:87], v[176:179], v[208:211], 0
	v_mul_f32_e32 v24, v230, v24
	v_mul_f32_e32 v25, v230, v25
	v_mul_f32_e32 v26, v230, v26
	v_mul_f32_e32 v27, v230, v27
	v_cvt_pk_bf16_f32 v28, v28, v29
	v_mfma_f32_16x16x32_bf16 v[80:83], v[184:187], v[208:211], 0
	v_cvt_pk_bf16_f32 v29, v30, v31
	v_cvt_pk_bf16_f32 v30, v24, v25
	v_cvt_pk_bf16_f32 v31, v26, v27
	global_store_dwordx4 v[232:233], v[28:31], off
	v_mul_f32_e32 v20, v230, v20
	v_mfma_f32_16x16x32_bf16 v[68:71], v[176:179], v[216:219], 0
	v_mul_f32_e32 v21, v230, v21
	v_mul_f32_e32 v22, v230, v22
	v_mul_f32_e32 v23, v230, v23
	v_mul_f32_e32 v16, v230, v16
	v_mul_f32_e32 v17, v230, v17
	v_mfma_f32_16x16x32_bf16 v[64:67], v[184:187], v[216:219], 0
	v_mul_f32_e32 v18, v230, v18
	v_mul_f32_e32 v19, v230, v19
	v_cvt_pk_bf16_f32 v20, v20, v21
	v_cvt_pk_bf16_f32 v21, v22, v23
	v_cvt_pk_bf16_f32 v22, v16, v17
	v_mfma_f32_16x16x32_bf16 v[116:119], v[180:183], v[196:199], v[116:119]
; #define PG8_STAGE(bufoff, gbase, voff) do { _Pragma("unroll") for (int _i = 0; _i < 2; ++_i) \
;         __builtin_amdgcn_global_load_lds((const unsigned*)((const char*)(gbase) + (voff)[_i]), (LAS unsigned*)(lds + (bufoff) + ldsw + _i * 8192), 16, 0, 0); } while (0)
; #define PG8_LDA(dst, b, h) do { _Pragma("unroll") for (int m = 0; m < 4; ++m) _Pragma("unroll") for (int k = 0; k < 2; ++k) dst[m][k] = *(const LAS bf16x8*)(lds + PG8_SA(b, h) + aoff + m * 2048 + k * 1024); } while (0)
; #define PG8_LDB(dst, b, h) do { _Pragma("unroll") for (int n = 0; n < 2; ++n) _Pragma("unroll") for (int k = 0; k < 2; ++k) dst[n][k] = *(const LAS bf16x8*)(lds + PG8_SB(b, h) + boff + n * 2048 + k * 1024); } while (0)
; #define PG8_MMA(ai, bj, At, Bt) do { __builtin_amdgcn_s_setprio(1); _Pragma("unroll") for (int k = 0; k < 2; ++k) _Pragma("unroll") for (int m = 0; m < 4; ++m) _Pragma("unroll") for (int n = 0; n < 2; ++n) \
;         acc[ai][bj][m][n] = __builtin_amdgcn_mfma_f32_16x16x32_bf16(Bt[n][k], At[m][k], acc[ai][bj][m][n], 0, 0, 0); __builtin_amdgcn_s_setprio(0); } while (0)
; #define PG8_WAIT_V(n) asm volatile("s_waitcnt vmcnt(" #n ")" ::: "memory")
; #define PG8_WAIT_L(n) asm volatile("s_waitcnt lgkmcnt(" #n ")" ::: "memory")
; #define PG8_BAR __builtin_amdgcn_s_barrier()
; template <class Epi, bool ALIGN_EPI>
; __device__ __forceinline__ void gemm_phase(LAS unsigned char* lds, const Gemm g, const StaticOrder& S, const Epi& E, const int tid) {
;     ...
;             PG8_WAIT_V(8); PG8_WAIT_L(0); PG8_BAR; PG8_MMA(0, 0, At, B0); PG8_MMA(0, 1, At, B1); PG8_BAR; PG8_SCHED;
;             PG8_LDA(At, 0, 1); PG8_STAGE(PG8_SB(0, 0), b2, voffB); PG8_STAGE(PG8_SB(0, 1), b2 + hB, voffB); PG8_STAGE(PG8_SA(0, 0), a2, voffA);
;             PG8_WAIT_V(8); PG8_WAIT_L(0); PG8_BAR; PG8_MMA(1, 0, At, B0); PG8_MMA(1, 1, At, B1); PG8_BAR; PG8_SCHED;
;             PG8_LDB(B0, 1, 0); PG8_LDB(B1, 1, 1); PG8_SCHED; PG8_LDA(At, 1, 0); PG8_STAGE(PG8_SA(0, 1), a2 + hA, voffA);
;             PG8_WAIT_V(8); PG8_WAIT_L(0); PG8_BAR; PG8_MMA(0, 0, At, B0); PG8_MMA(0, 1, At, B1); PG8_BAR; PG8_SCHED;
;             PG8_LDA(At, 1, 1); PG8_STAGE(PG8_SB(1, 0), b3, voffB); PG8_STAGE(PG8_SB(1, 1), b3 + hB, voffB); PG8_STAGE(PG8_SA(1, 0), a3, voffA);
;             PG8_WAIT_V(8); PG8_WAIT_L(0); PG8_BAR; PG8_MMA(1, 0, At, B0); PG8_MMA(1, 1, At, B1); PG8_BAR; PG8_SCHED;
	v_cvt_pk_bf16_f32 v23, v18, v19
	global_store_dwordx4 v[232:233], v[20:23], off offset:256
	v_lshl_add_u64 v[232:233], v[232:233], 0, s[98:99]
	v_mul_f32_e32 v12, v231, v12
	v_mul_f32_e32 v13, v231, v13
	v_mfma_f32_16x16x32_bf16 v[112:115], v[188:191], v[196:199], v[112:115]
	v_mul_f32_e32 v14, v231, v14
	v_mul_f32_e32 v15, v231, v15
	v_mul_f32_e32 v8, v231, v8
	v_mul_f32_e32 v9, v231, v9
	v_mul_f32_e32 v10, v231, v10
	v_mfma_f32_16x16x32_bf16 v[100:103], v[180:183], v[204:207], v[100:103]
	v_mul_f32_e32 v11, v231, v11
	v_cvt_pk_bf16_f32 v12, v12, v13
	v_cvt_pk_bf16_f32 v13, v14, v15
	v_cvt_pk_bf16_f32 v14, v8, v9
	v_cvt_pk_bf16_f32 v15, v10, v11
	v_mfma_f32_16x16x32_bf16 v[96:99], v[188:191], v[204:207], v[96:99]
	global_store_dwordx4 v[232:233], v[12:15], off
	v_mul_f32_e32 v4, v231, v4
	v_mul_f32_e32 v5, v231, v5
	v_mul_f32_e32 v6, v231, v6
	v_mul_f32_e32 v7, v231, v7
	v_mfma_f32_16x16x32_bf16 v[84:87], v[180:183], v[212:215], v[84:87]
	v_mul_f32_e32 v0, v231, v0
	v_mul_f32_e32 v1, v231, v1
	v_mul_f32_e32 v2, v231, v2
	v_mul_f32_e32 v3, v231, v3
	v_cvt_pk_bf16_f32 v4, v4, v5
	v_mfma_f32_16x16x32_bf16 v[80:83], v[188:191], v[212:215], v[80:83]
	v_cvt_pk_bf16_f32 v5, v6, v7
	v_cvt_pk_bf16_f32 v6, v0, v1
	v_cvt_pk_bf16_f32 v7, v2, v3
	global_store_dwordx4 v[232:233], v[4:7], off offset:256
	v_mfma_f32_16x16x32_bf16 v[68:71], v[180:183], v[240:243], v[68:71]
	v_mfma_f32_16x16x32_bf16 v[64:67], v[188:191], v[240:243], v[64:67]
	s_setprio 0
	s_barrier
	s_add_i32 s62, s33, s45
	v_lshl_add_u64 v[244:245], v[220:221], 0, v[168:169]
	s_mov_b32 m0, s62
	ds_read_b128 v[192:195], v151 offset:16384
	ds_read_b128 v[196:199], v151 offset:17408
	ds_read_b128 v[200:203], v151 offset:18432
	ds_read_b128 v[204:207], v151 offset:19456
	ds_read_b128 v[208:211], v151 offset:20480
	ds_read_b128 v[212:215], v151 offset:21504
	ds_read_b128 v[216:219], v151 offset:22528
	ds_read_b128 v[240:243], v151 offset:23552
	global_load_lds_dwordx4 v[244:245], off
	v_lshl_add_u64 v[246:247], v[220:221], 0, v[128:129]
	s_add_i32 m0, s62, 0x2000
	v_lshl_add_u64 v[220:221], v[220:221], 0, s[12:13]
	s_add_i32 s10, s10, s45
	global_load_lds_dwordx4 v[246:247], off
	v_lshl_add_u64 v[248:249], v[220:221], 0, v[168:169]
	s_mov_b32 m0, s10
	v_lshl_add_u64 v[220:221], v[220:221], 0, v[128:129]
	global_load_lds_dwordx4 v[248:249], off
	s_add_i32 m0, s10, 0x2000
	v_lshl_add_u64 v[250:251], v[146:147], 0, v[132:133]
	global_load_lds_dwordx4 v[220:221], off
	s_mov_b32 m0, s25
	v_lshl_add_u64 v[252:253], v[146:147], 0, v[130:131]
	global_load_lds_dwordx4 v[250:251], off
	s_mov_b32 m0, s50
	s_nop 0
	global_load_lds_dwordx4 v[252:253], off
	s_waitcnt vmcnt(24)
	s_waitcnt lgkmcnt(0)
	s_barrier
	s_setprio 1
	s_waitcnt lgkmcnt(0)
	v_mfma_f32_16x16x32_bf16 v[60:63], v[152:155], v[192:195], 0
	v_mfma_f32_16x16x32_bf16 v[56:59], v[160:163], v[192:195], 0
	v_mfma_f32_16x16x32_bf16 v[44:47], v[152:155], v[200:203], 0
	v_mfma_f32_16x16x32_bf16 v[40:43], v[160:163], v[200:203], 0
	v_mfma_f32_16x16x32_bf16 v[28:31], v[152:155], v[208:211], 0
	v_mfma_f32_16x16x32_bf16 v[24:27], v[160:163], v[208:211], 0
	v_mfma_f32_16x16x32_bf16 v[12:15], v[152:155], v[216:219], 0
	v_mfma_f32_16x16x32_bf16 v[8:11], v[160:163], v[216:219], 0
	v_mfma_f32_16x16x32_bf16 v[60:63], v[156:159], v[196:199], v[60:63]
	v_mfma_f32_16x16x32_bf16 v[56:59], v[164:167], v[196:199], v[56:59]
	v_mfma_f32_16x16x32_bf16 v[44:47], v[156:159], v[204:207], v[44:47]
	v_mfma_f32_16x16x32_bf16 v[40:43], v[164:167], v[204:207], v[40:43]
	v_mfma_f32_16x16x32_bf16 v[28:31], v[156:159], v[212:215], v[28:31]
	v_mfma_f32_16x16x32_bf16 v[24:27], v[164:167], v[212:215], v[24:27]
	v_mfma_f32_16x16x32_bf16 v[12:15], v[156:159], v[240:243], v[12:15]
	v_mfma_f32_16x16x32_bf16 v[8:11], v[164:167], v[240:243], v[8:11]
	s_setprio 0
	s_setprio 1
	v_mfma_f32_16x16x32_bf16 v[52:55], v[176:179], v[192:195], 0
	v_mfma_f32_16x16x32_bf16 v[48:51], v[184:187], v[192:195], 0
	v_mfma_f32_16x16x32_bf16 v[36:39], v[176:179], v[200:203], 0
	v_mfma_f32_16x16x32_bf16 v[32:35], v[184:187], v[200:203], 0
	v_mfma_f32_16x16x32_bf16 v[20:23], v[176:179], v[208:211], 0
	v_mfma_f32_16x16x32_bf16 v[16:19], v[184:187], v[208:211], 0
	v_mfma_f32_16x16x32_bf16 v[4:7], v[176:179], v[216:219], 0
	v_mfma_f32_16x16x32_bf16 v[0:3], v[184:187], v[216:219], 0
	v_mfma_f32_16x16x32_bf16 v[52:55], v[180:183], v[196:199], v[52:55]
	v_mfma_f32_16x16x32_bf16 v[48:51], v[188:191], v[196:199], v[48:51]
	v_mfma_f32_16x16x32_bf16 v[36:39], v[180:183], v[204:207], v[36:39]
	v_mfma_f32_16x16x32_bf16 v[32:35], v[188:191], v[204:207], v[32:35]
	v_mfma_f32_16x16x32_bf16 v[20:23], v[180:183], v[212:215], v[20:23]
	v_mfma_f32_16x16x32_bf16 v[16:19], v[188:191], v[212:215], v[16:19]
	v_mfma_f32_16x16x32_bf16 v[4:7], v[180:183], v[240:243], v[4:7]
	v_mfma_f32_16x16x32_bf16 v[0:3], v[188:191], v[240:243], v[0:3]
	s_setprio 0
	s_barrier
	s_add_i32 s10, 0, 0x18000
	v_add_u32_e32 v148, s10, v149
	s_add_i32 s62, 0, 0x1c000
	ds_read_b128 v[152:155], v148
	ds_read_b128 v[156:159], v148 offset:1024
	ds_read_b128 v[160:163], v148 offset:2048
	ds_read_b128 v[164:167], v148 offset:3072
	v_add_u32_e32 v148, s62, v149
	ds_read_b128 v[176:179], v148
	ds_read_b128 v[180:183], v148 offset:1024
	ds_read_b128 v[184:187], v148 offset:2048
	ds_read_b128 v[188:191], v148 offset:3072
	v_lshl_add_u64 v[146:147], v[146:147], 0, s[94:95]
	s_mov_b32 m0, s51
	v_lshl_add_u64 v[226:227], v[146:147], 0, v[132:133]
	ds_read_b128 v[192:195], v151 offset:32768
	ds_read_b128 v[196:199], v151 offset:33792
	ds_read_b128 v[200:203], v151 offset:34816
	ds_read_b128 v[204:207], v151 offset:35840
	ds_read_b128 v[208:211], v151 offset:36864
	ds_read_b128 v[212:215], v151 offset:37888
	ds_read_b128 v[216:219], v151 offset:38912
	ds_read_b128 v[240:243], v151 offset:39936
	global_load_lds_dwordx4 v[226:227], off
	v_lshl_add_u64 v[146:147], v[146:147], 0, v[130:131]
	s_mov_b32 m0, s52
	s_nop 0
	global_load_lds_dwordx4 v[146:147], off
	s_waitcnt vmcnt(16)
	s_waitcnt lgkmcnt(0)
	s_barrier
; #define PG8_STAGE(bufoff, gbase, voff) do { _Pragma("unroll") for (int _i = 0; _i < 2; ++_i) \
;         __builtin_amdgcn_global_load_lds((const unsigned*)((const char*)(gbase) + (voff)[_i]), (LAS unsigned*)(lds + (bufoff) + ldsw + _i * 8192), 16, 0, 0); } while (0)
; #define PG8_LDA(dst, b, h) do { _Pragma("unroll") for (int m = 0; m < 4; ++m) _Pragma("unroll") for (int k = 0; k < 2; ++k) dst[m][k] = *(const LAS bf16x8*)(lds + PG8_SA(b, h) + aoff + m * 2048 + k * 1024); } while (0)
; #define PG8_LDB(dst, b, h) do { _Pragma("unroll") for (int n = 0; n < 2; ++n) _Pragma("unroll") for (int k = 0; k < 2; ++k) dst[n][k] = *(const LAS bf16x8*)(lds + PG8_SB(b, h) + boff + n * 2048 + k * 1024); } while (0)
; #define PG8_MMA(ai, bj, At, Bt) do { __builtin_amdgcn_s_setprio(1); _Pragma("unroll") for (int k = 0; k < 2; ++k) _Pragma("unroll") for (int m = 0; m < 4; ++m) _Pragma("unroll") for (int n = 0; n < 2; ++n) \
;         acc[ai][bj][m][n] = __builtin_amdgcn_mfma_f32_16x16x32_bf16(Bt[n][k], At[m][k], acc[ai][bj][m][n], 0, 0, 0); __builtin_amdgcn_s_setprio(0); } while (0)
; #define PG8_WAIT_V(n) asm volatile("s_waitcnt vmcnt(" #n ")" ::: "memory")
; #define PG8_WAIT_L(n) asm volatile("s_waitcnt lgkmcnt(" #n ")" ::: "memory")
; #define PG8_BAR __builtin_amdgcn_s_barrier()
; #define PG8_SCHED __builtin_amdgcn_sched_barrier(0)
; template <class Epi, bool ALIGN_EPI>
; __device__ __forceinline__ void gemm_phase(LAS unsigned char* lds, const Gemm g, const StaticOrder& S, const Epi& E, const int tid) {
;     ...
;             PG8_WAIT_V(8); PG8_WAIT_L(0); PG8_BAR; PG8_MMA(1, 0, At, B0); PG8_MMA(1, 1, At, B1); PG8_BAR; PG8_SCHED;
;             PG8_LDB(B0, 1, 0); PG8_LDB(B1, 1, 1); PG8_SCHED; PG8_LDA(At, 1, 0); PG8_STAGE(PG8_SA(0, 1), a2 + hA, voffA);
;             PG8_WAIT_V(8); PG8_WAIT_L(0); PG8_BAR; PG8_MMA(0, 0, At, B0); PG8_MMA(0, 1, At, B1); PG8_BAR; PG8_SCHED;
;             PG8_LDA(At, 1, 1); PG8_STAGE(PG8_SB(1, 0), b3, voffB); PG8_STAGE(PG8_SB(1, 1), b3 + hB, voffB); PG8_STAGE(PG8_SA(1, 0), a3, voffA);
;             PG8_WAIT_V(8); PG8_WAIT_L(0); PG8_BAR; PG8_MMA(1, 0, At, B0); PG8_MMA(1, 1, At, B1); PG8_BAR; PG8_SCHED;
;         }
	s_setprio 1
	s_waitcnt lgkmcnt(0)
	v_mfma_f32_16x16x32_bf16 v[124:127], v[152:155], v[192:195], v[124:127]
	v_mfma_f32_16x16x32_bf16 v[120:123], v[160:163], v[192:195], v[120:123]
	v_mfma_f32_16x16x32_bf16 v[108:111], v[152:155], v[200:203], v[108:111]
	v_mfma_f32_16x16x32_bf16 v[104:107], v[160:163], v[200:203], v[104:107]
	v_mfma_f32_16x16x32_bf16 v[92:95], v[152:155], v[208:211], v[92:95]
	v_mfma_f32_16x16x32_bf16 v[88:91], v[160:163], v[208:211], v[88:91]
	v_mfma_f32_16x16x32_bf16 v[76:79], v[152:155], v[216:219], v[76:79]
	v_mfma_f32_16x16x32_bf16 v[72:75], v[160:163], v[216:219], v[72:75]
	v_mfma_f32_16x16x32_bf16 v[124:127], v[156:159], v[196:199], v[124:127]
	v_mfma_f32_16x16x32_bf16 v[120:123], v[164:167], v[196:199], v[120:123]
	v_mfma_f32_16x16x32_bf16 v[108:111], v[156:159], v[204:207], v[108:111]
	v_mfma_f32_16x16x32_bf16 v[104:107], v[164:167], v[204:207], v[104:107]
	v_mfma_f32_16x16x32_bf16 v[92:95], v[156:159], v[212:215], v[92:95]
	v_mfma_f32_16x16x32_bf16 v[88:91], v[164:167], v[212:215], v[88:91]
	v_mfma_f32_16x16x32_bf16 v[76:79], v[156:159], v[240:243], v[76:79]
	v_mfma_f32_16x16x32_bf16 v[72:75], v[164:167], v[240:243], v[72:75]
	s_setprio 0
	s_setprio 1
	v_mfma_f32_16x16x32_bf16 v[116:119], v[176:179], v[192:195], v[116:119]
	v_mfma_f32_16x16x32_bf16 v[112:115], v[184:187], v[192:195], v[112:115]
	v_mfma_f32_16x16x32_bf16 v[100:103], v[176:179], v[200:203], v[100:103]
	v_mfma_f32_16x16x32_bf16 v[96:99], v[184:187], v[200:203], v[96:99]
	v_mfma_f32_16x16x32_bf16 v[84:87], v[176:179], v[208:211], v[84:87]
	v_mfma_f32_16x16x32_bf16 v[80:83], v[184:187], v[208:211], v[80:83]
	v_mfma_f32_16x16x32_bf16 v[68:71], v[176:179], v[216:219], v[68:71]
	v_mfma_f32_16x16x32_bf16 v[64:67], v[184:187], v[216:219], v[64:67]
	v_mfma_f32_16x16x32_bf16 v[116:119], v[180:183], v[196:199], v[116:119]
	v_mfma_f32_16x16x32_bf16 v[112:115], v[188:191], v[196:199], v[112:115]
	v_mfma_f32_16x16x32_bf16 v[100:103], v[180:183], v[204:207], v[100:103]
	v_mfma_f32_16x16x32_bf16 v[96:99], v[188:191], v[204:207], v[96:99]
	v_mfma_f32_16x16x32_bf16 v[84:87], v[180:183], v[212:215], v[84:87]
	v_mfma_f32_16x16x32_bf16 v[80:83], v[188:191], v[212:215], v[80:83]
	v_mfma_f32_16x16x32_bf16 v[68:71], v[180:183], v[240:243], v[68:71]
	v_mfma_f32_16x16x32_bf16 v[64:67], v[188:191], v[240:243], v[64:67]
	s_setprio 0
	s_barrier
	s_add_i32 s10, s10, s45
	v_lshl_add_u64 v[146:147], v[244:245], 0, s[92:93]
	s_mov_b32 m0, s10
	ds_read_b128 v[192:195], v151 offset:49152
	ds_read_b128 v[196:199], v151 offset:50176
	ds_read_b128 v[200:203], v151 offset:51200
	ds_read_b128 v[204:207], v151 offset:52224
	ds_read_b128 v[208:211], v151 offset:53248
	ds_read_b128 v[212:215], v151 offset:54272
	ds_read_b128 v[216:219], v151 offset:55296
	ds_read_b128 v[240:243], v151 offset:56320
	global_load_lds_dwordx4 v[146:147], off
	v_lshl_add_u64 v[146:147], v[246:247], 0, s[92:93]
	s_add_i32 m0, s10, 0x2000
	s_add_i32 s10, s62, s45
	global_load_lds_dwordx4 v[146:147], off
	v_lshl_add_u64 v[146:147], v[248:249], 0, s[92:93]
	s_mov_b32 m0, s10
	s_nop 0
	global_load_lds_dwordx4 v[146:147], off
	v_lshl_add_u64 v[146:147], v[220:221], 0, s[92:93]
	s_add_i32 m0, s10, 0x2000
	s_nop 0
	global_load_lds_dwordx4 v[146:147], off
	v_lshl_add_u64 v[146:147], v[250:251], 0, s[92:93]
	s_mov_b32 m0, s53
	s_nop 0
	global_load_lds_dwordx4 v[146:147], off
	v_lshl_add_u64 v[146:147], v[252:253], 0, s[92:93]
	s_mov_b32 m0, s54
	s_nop 0
	global_load_lds_dwordx4 v[146:147], off
	s_waitcnt vmcnt(8)
	s_waitcnt lgkmcnt(0)
	s_barrier
	s_setprio 1
	s_waitcnt lgkmcnt(0)
	v_mfma_f32_16x16x32_bf16 v[60:63], v[152:155], v[192:195], v[60:63]
	v_mfma_f32_16x16x32_bf16 v[56:59], v[160:163], v[192:195], v[56:59]
	v_mfma_f32_16x16x32_bf16 v[44:47], v[152:155], v[200:203], v[44:47]
	v_mfma_f32_16x16x32_bf16 v[40:43], v[160:163], v[200:203], v[40:43]
	v_mfma_f32_16x16x32_bf16 v[28:31], v[152:155], v[208:211], v[28:31]
	v_mfma_f32_16x16x32_bf16 v[24:27], v[160:163], v[208:211], v[24:27]
	v_mfma_f32_16x16x32_bf16 v[12:15], v[152:155], v[216:219], v[12:15]
	v_mfma_f32_16x16x32_bf16 v[8:11], v[160:163], v[216:219], v[8:11]
	v_mfma_f32_16x16x32_bf16 v[60:63], v[156:159], v[196:199], v[60:63]
	v_mfma_f32_16x16x32_bf16 v[56:59], v[164:167], v[196:199], v[56:59]
	v_mfma_f32_16x16x32_bf16 v[44:47], v[156:159], v[204:207], v[44:47]
	v_mfma_f32_16x16x32_bf16 v[40:43], v[164:167], v[204:207], v[40:43]
	v_mfma_f32_16x16x32_bf16 v[28:31], v[156:159], v[212:215], v[28:31]
	v_mfma_f32_16x16x32_bf16 v[24:27], v[164:167], v[212:215], v[24:27]
	v_mfma_f32_16x16x32_bf16 v[12:15], v[156:159], v[240:243], v[12:15]
	v_mfma_f32_16x16x32_bf16 v[8:11], v[164:167], v[240:243], v[8:11]
	s_setprio 0
	s_setprio 1
	v_mfma_f32_16x16x32_bf16 v[52:55], v[176:179], v[192:195], v[52:55]
	v_mfma_f32_16x16x32_bf16 v[48:51], v[184:187], v[192:195], v[48:51]
	v_mfma_f32_16x16x32_bf16 v[36:39], v[176:179], v[200:203], v[36:39]
	v_mfma_f32_16x16x32_bf16 v[32:35], v[184:187], v[200:203], v[32:35]
	v_mfma_f32_16x16x32_bf16 v[20:23], v[176:179], v[208:211], v[20:23]
	v_mfma_f32_16x16x32_bf16 v[16:19], v[184:187], v[208:211], v[16:19]
	v_mfma_f32_16x16x32_bf16 v[4:7], v[176:179], v[216:219], v[4:7]
	v_mfma_f32_16x16x32_bf16 v[0:3], v[184:187], v[216:219], v[0:3]
	v_mfma_f32_16x16x32_bf16 v[52:55], v[180:183], v[196:199], v[52:55]
	v_mfma_f32_16x16x32_bf16 v[48:51], v[188:191], v[196:199], v[48:51]
	v_mfma_f32_16x16x32_bf16 v[36:39], v[180:183], v[204:207], v[36:39]
	v_mfma_f32_16x16x32_bf16 v[32:35], v[188:191], v[204:207], v[32:35]
	v_mfma_f32_16x16x32_bf16 v[20:23], v[180:183], v[212:215], v[20:23]
	v_mfma_f32_16x16x32_bf16 v[16:19], v[188:191], v[212:215], v[16:19]
	v_mfma_f32_16x16x32_bf16 v[4:7], v[180:183], v[240:243], v[4:7]
	v_mfma_f32_16x16x32_bf16 v[0:3], v[188:191], v[240:243], v[0:3]
	s_setprio 0
	s_barrier
	v_lshl_add_u64 v[142:143], v[142:143], 0, s[80:81]
	v_lshl_add_u64 v[144:145], v[144:145], 0, s[80:81]
	s_mov_b32 s10, s11
	s_cmp_eq_u32 s10, s55
	s_cbranch_scc1 .Lq5_last
	s_branch .LBB0_354

; #define PG8_STAGE(bufoff, gbase, voff) do { _Pragma("unroll") for (int _i = 0; _i < 2; ++_i) \
;         __builtin_amdgcn_global_load_lds((const unsigned*)((const char*)(gbase) + (voff)[_i]), (LAS unsigned*)(lds + (bufoff) + ldsw + _i * 8192), 16, 0, 0); } while (0)
; #define PG8_LDA(dst, b, h) do { _Pragma("unroll") for (int m = 0; m < 4; ++m) _Pragma("unroll") for (int k = 0; k < 2; ++k) dst[m][k] = *(const LAS bf16x8*)(lds + PG8_SA(b, h) + aoff + m * 2048 + k * 1024); } while (0)
; #define PG8_LDB(dst, b, h) do { _Pragma("unroll") for (int n = 0; n < 2; ++n) _Pragma("unroll") for (int k = 0; k < 2; ++k) dst[n][k] = *(const LAS bf16x8*)(lds + PG8_SB(b, h) + boff + n * 2048 + k * 1024); } while (0)
; #define PG8_MMA(ai, bj, At, Bt) do { __builtin_amdgcn_s_setprio(1); _Pragma("unroll") for (int k = 0; k < 2; ++k) _Pragma("unroll") for (int m = 0; m < 4; ++m) _Pragma("unroll") for (int n = 0; n < 2; ++n) \
;         acc[ai][bj][m][n] = __builtin_amdgcn_mfma_f32_16x16x32_bf16(Bt[n][k], At[m][k], acc[ai][bj][m][n], 0, 0, 0); __builtin_amdgcn_s_setprio(0); } while (0)
; template <class Epi, bool ALIGN_EPI>
; __device__ __forceinline__ void gemm_phase(LAS unsigned char* lds, const Gemm g, const StaticOrder& S, const Epi& E, const int tid) {
;     ...
;         for (int t = 0; t < nt; t += 2) {
;             const bool last = (t == nt - 2);
;             const char* a1 = cA + (size_t)(t + 1) * kstep;
;             const char* a2 = last ? nA : cA + (size_t)(t + 2) * kstep; const char* b2 = last ? nB : cB + (size_t)(t + 2) * kstep;
;             const char* a3 = a2 + kstep; const char* b3 = b2 + kstep;
;             PG8_LDB(B0, 0, 0); PG8_LDB(B1, 0, 1); PG8_SCHED; PG8_LDA(At, 0, 0); PG8_STAGE(PG8_SA(1, 1), a1 + hA, voffA);
;             PG8_WAIT_V(8); PG8_WAIT_L(0); PG8_BAR; PG8_MMA(0, 0, At, B0); PG8_MMA(0, 1, At, B1); PG8_BAR; PG8_SCHED;
;             PG8_LDA(At, 0, 1); PG8_STAGE(PG8_SB(0, 0), b2, voffB); PG8_STAGE(PG8_SB(0, 1), b2 + hB, voffB); PG8_STAGE(PG8_SA(0, 0), a2, voffA);
;             PG8_WAIT_V(8); PG8_WAIT_L(0); PG8_BAR; PG8_MMA(1, 0, At, B0); PG8_MMA(1, 1, At, B1); PG8_BAR; PG8_SCHED;
;             PG8_LDB(B0, 1, 0); PG8_LDB(B1, 1, 1); PG8_SCHED; PG8_LDA(At, 1, 0); PG8_STAGE(PG8_SA(0, 1), a2 + hA, voffA);
;             PG8_WAIT_V(8); PG8_WAIT_L(0); PG8_BAR; PG8_MMA(0, 0, At, B0); PG8_MMA(0, 1, At, B1); PG8_BAR; PG8_SCHED;
.Lq5_last:
	s_add_i32 s11, s10, 2
	s_cmp_eq_u32 s55, s10
	s_cselect_b64 vcc, -1, 0
	v_add_u32_e32 v148, s33, v149
	s_add_i32 s10, 0, 0x14000
	ds_read_b128 v[152:155], v148
	ds_read_b128 v[156:159], v148 offset:1024
	ds_read_b128 v[160:163], v148 offset:2048
	ds_read_b128 v[164:167], v148 offset:3072
	v_add_u32_e32 v148, s10, v149
	ds_read_b128 v[176:179], v148
	ds_read_b128 v[180:183], v148 offset:1024
	ds_read_b128 v[184:187], v148 offset:2048
	ds_read_b128 v[188:191], v148 offset:3072
	v_lshl_add_u64 v[146:147], v[142:143], 0, s[92:93]
	v_cndmask_b32_e32 v147, v147, v139, vcc
	v_cndmask_b32_e32 v146, v146, v138, vcc
	v_cndmask_b32_e32 v221, v145, v141, vcc
	v_cndmask_b32_e32 v220, v144, v140, vcc
	v_lshl_add_u64 v[244:245], v[142:143], 0, v[134:135]
	s_add_i32 m0, s25, 0xc000
	ds_read_b128 v[192:195], v151
	ds_read_b128 v[196:199], v151 offset:1024
	ds_read_b128 v[200:203], v151 offset:2048
	ds_read_b128 v[204:207], v151 offset:3072
	ds_read_b128 v[208:211], v151 offset:4096
	ds_read_b128 v[212:215], v151 offset:5120
	ds_read_b128 v[216:219], v151 offset:6144
	ds_read_b128 v[240:243], v151 offset:7168
	global_load_lds_dwordx4 v[244:245], off
	v_lshl_add_u64 v[244:245], v[142:143], 0, v[136:137]
	s_add_i32 m0, s25, 0xe000
	s_nop 0
	global_load_lds_dwordx4 v[244:245], off
	s_waitcnt vmcnt(8)
	s_waitcnt lgkmcnt(0)
	s_barrier
	s_setprio 1
	s_waitcnt lgkmcnt(0)
	v_mfma_f32_16x16x32_bf16 v[124:127], v[152:155], v[192:195], v[124:127]
	v_mfma_f32_16x16x32_bf16 v[120:123], v[160:163], v[192:195], v[120:123]
	v_mfma_f32_16x16x32_bf16 v[108:111], v[152:155], v[200:203], v[108:111]
	v_mfma_f32_16x16x32_bf16 v[104:107], v[160:163], v[200:203], v[104:107]
	v_mfma_f32_16x16x32_bf16 v[92:95], v[152:155], v[208:211], v[92:95]
	v_mfma_f32_16x16x32_bf16 v[88:91], v[160:163], v[208:211], v[88:91]
	v_mfma_f32_16x16x32_bf16 v[76:79], v[152:155], v[216:219], v[76:79]
	v_mfma_f32_16x16x32_bf16 v[72:75], v[160:163], v[216:219], v[72:75]
	v_mfma_f32_16x16x32_bf16 v[124:127], v[156:159], v[196:199], v[124:127]
	v_mfma_f32_16x16x32_bf16 v[120:123], v[164:167], v[196:199], v[120:123]
	v_mfma_f32_16x16x32_bf16 v[108:111], v[156:159], v[204:207], v[108:111]
	v_mfma_f32_16x16x32_bf16 v[104:107], v[164:167], v[204:207], v[104:107]
	v_mfma_f32_16x16x32_bf16 v[92:95], v[156:159], v[212:215], v[92:95]
	v_mfma_f32_16x16x32_bf16 v[88:91], v[164:167], v[212:215], v[88:91]
	v_mfma_f32_16x16x32_bf16 v[76:79], v[156:159], v[240:243], v[76:79]
	v_mfma_f32_16x16x32_bf16 v[72:75], v[164:167], v[240:243], v[72:75]
	s_setprio 0
	s_setprio 1
	v_mfma_f32_16x16x32_bf16 v[116:119], v[176:179], v[192:195], v[116:119]
	v_mfma_f32_16x16x32_bf16 v[112:115], v[184:187], v[192:195], v[112:115]
	v_mfma_f32_16x16x32_bf16 v[100:103], v[176:179], v[200:203], v[100:103]
	v_mfma_f32_16x16x32_bf16 v[96:99], v[184:187], v[200:203], v[96:99]
	v_mfma_f32_16x16x32_bf16 v[84:87], v[176:179], v[208:211], v[84:87]
	v_mfma_f32_16x16x32_bf16 v[80:83], v[184:187], v[208:211], v[80:83]
	v_mfma_f32_16x16x32_bf16 v[68:71], v[176:179], v[216:219], v[68:71]
	v_mfma_f32_16x16x32_bf16 v[64:67], v[184:187], v[216:219], v[64:67]
	v_mfma_f32_16x16x32_bf16 v[116:119], v[180:183], v[196:199], v[116:119]
	v_mfma_f32_16x16x32_bf16 v[112:115], v[188:191], v[196:199], v[112:115]
	v_mfma_f32_16x16x32_bf16 v[100:103], v[180:183], v[204:207], v[100:103]
	v_mfma_f32_16x16x32_bf16 v[96:99], v[188:191], v[204:207], v[96:99]
	v_mfma_f32_16x16x32_bf16 v[84:87], v[180:183], v[212:215], v[84:87]
	v_mfma_f32_16x16x32_bf16 v[80:83], v[188:191], v[212:215], v[80:83]
	v_mfma_f32_16x16x32_bf16 v[68:71], v[180:183], v[240:243], v[68:71]
	v_mfma_f32_16x16x32_bf16 v[64:67], v[188:191], v[240:243], v[64:67]
	s_setprio 0
	s_barrier
	s_add_i32 s62, s33, s45
	v_lshl_add_u64 v[244:245], v[220:221], 0, v[168:169]
	s_mov_b32 m0, s62
	ds_read_b128 v[192:195], v151 offset:16384
	ds_read_b128 v[196:199], v151 offset:17408
	ds_read_b128 v[200:203], v151 offset:18432
	ds_read_b128 v[204:207], v151 offset:19456
	ds_read_b128 v[208:211], v151 offset:20480
	ds_read_b128 v[212:215], v151 offset:21504
	ds_read_b128 v[216:219], v151 offset:22528
	ds_read_b128 v[240:243], v151 offset:23552
	global_load_lds_dwordx4 v[244:245], off
	v_lshl_add_u64 v[246:247], v[220:221], 0, v[128:129]
	s_add_i32 m0, s62, 0x2000
	v_lshl_add_u64 v[220:221], v[220:221], 0, s[12:13]
	s_add_i32 s10, s10, s45
	global_load_lds_dwordx4 v[246:247], off
	v_lshl_add_u64 v[248:249], v[220:221], 0, v[168:169]
	s_mov_b32 m0, s10
	v_lshl_add_u64 v[220:221], v[220:221], 0, v[128:129]
	global_load_lds_dwordx4 v[248:249], off
	s_add_i32 m0, s10, 0x2000
	v_lshl_add_u64 v[250:251], v[146:147], 0, v[132:133]
	global_load_lds_dwordx4 v[220:221], off
	s_mov_b32 m0, s25
	v_lshl_add_u64 v[252:253], v[146:147], 0, v[130:131]
	global_load_lds_dwordx4 v[250:251], off
	s_mov_b32 m0, s50
	s_nop 0
	global_load_lds_dwordx4 v[252:253], off
	s_waitcnt vmcnt(8)
	s_waitcnt lgkmcnt(0)
	s_barrier
; #define PG8_STAGE(bufoff, gbase, voff) do { _Pragma("unroll") for (int _i = 0; _i < 2; ++_i) \
;         __builtin_amdgcn_global_load_lds((const unsigned*)((const char*)(gbase) + (voff)[_i]), (LAS unsigned*)(lds + (bufoff) + ldsw + _i * 8192), 16, 0, 0); } while (0)
; #define PG8_LDA(dst, b, h) do { _Pragma("unroll") for (int m = 0; m < 4; ++m) _Pragma("unroll") for (int k = 0; k < 2; ++k) dst[m][k] = *(const LAS bf16x8*)(lds + PG8_SA(b, h) + aoff + m * 2048 + k * 1024); } while (0)
; #define PG8_LDB(dst, b, h) do { _Pragma("unroll") for (int n = 0; n < 2; ++n) _Pragma("unroll") for (int k = 0; k < 2; ++k) dst[n][k] = *(const LAS bf16x8*)(lds + PG8_SB(b, h) + boff + n * 2048 + k * 1024); } while (0)
; #define PG8_MMA(ai, bj, At, Bt) do { __builtin_amdgcn_s_setprio(1); _Pragma("unroll") for (int k = 0; k < 2; ++k) _Pragma("unroll") for (int m = 0; m < 4; ++m) _Pragma("unroll") for (int n = 0; n < 2; ++n) \
;         acc[ai][bj][m][n] = __builtin_amdgcn_mfma_f32_16x16x32_bf16(Bt[n][k], At[m][k], acc[ai][bj][m][n], 0, 0, 0); __builtin_amdgcn_s_setprio(0); } while (0)
; #define PG8_WAIT_V(n) asm volatile("s_waitcnt vmcnt(" #n ")" ::: "memory")
; #define PG8_WAIT_L(n) asm volatile("s_waitcnt lgkmcnt(" #n ")" ::: "memory")
; #define PG8_BAR __builtin_amdgcn_s_barrier()
; #define PG8_SCHED __builtin_amdgcn_sched_barrier(0)
; template <class Epi, bool ALIGN_EPI>
; __device__ __forceinline__ void gemm_phase(LAS unsigned char* lds, const Gemm g, const StaticOrder& S, const Epi& E, const int tid) {
;     ...
;             PG8_WAIT_V(8); PG8_WAIT_L(0); PG8_BAR; PG8_MMA(1, 0, At, B0); PG8_MMA(1, 1, At, B1); PG8_BAR; PG8_SCHED;
;             PG8_LDB(B0, 1, 0); PG8_LDB(B1, 1, 1); PG8_SCHED; PG8_LDA(At, 1, 0); PG8_STAGE(PG8_SA(0, 1), a2 + hA, voffA);
;             PG8_WAIT_V(8); PG8_WAIT_L(0); PG8_BAR; PG8_MMA(0, 0, At, B0); PG8_MMA(0, 1, At, B1); PG8_BAR; PG8_SCHED;
;             PG8_LDA(At, 1, 1); PG8_STAGE(PG8_SB(1, 0), b3, voffB); PG8_STAGE(PG8_SB(1, 1), b3 + hB, voffB); PG8_STAGE(PG8_SA(1, 0), a3, voffA);
;             PG8_WAIT_V(8); PG8_WAIT_L(0); PG8_BAR; PG8_MMA(1, 0, At, B0); PG8_MMA(1, 1, At, B1); PG8_BAR; PG8_SCHED;
	s_setprio 1
	s_waitcnt lgkmcnt(0)
	v_mfma_f32_16x16x32_bf16 v[60:63], v[152:155], v[192:195], v[60:63]
	v_mfma_f32_16x16x32_bf16 v[56:59], v[160:163], v[192:195], v[56:59]
	v_mfma_f32_16x16x32_bf16 v[44:47], v[152:155], v[200:203], v[44:47]
	v_mfma_f32_16x16x32_bf16 v[40:43], v[160:163], v[200:203], v[40:43]
	v_mfma_f32_16x16x32_bf16 v[28:31], v[152:155], v[208:211], v[28:31]
	v_mfma_f32_16x16x32_bf16 v[24:27], v[160:163], v[208:211], v[24:27]
	v_mfma_f32_16x16x32_bf16 v[12:15], v[152:155], v[216:219], v[12:15]
	v_mfma_f32_16x16x32_bf16 v[8:11], v[160:163], v[216:219], v[8:11]
	v_mfma_f32_16x16x32_bf16 v[60:63], v[156:159], v[196:199], v[60:63]
	v_mfma_f32_16x16x32_bf16 v[56:59], v[164:167], v[196:199], v[56:59]
	v_mfma_f32_16x16x32_bf16 v[44:47], v[156:159], v[204:207], v[44:47]
	v_mfma_f32_16x16x32_bf16 v[40:43], v[164:167], v[204:207], v[40:43]
	v_mfma_f32_16x16x32_bf16 v[28:31], v[156:159], v[212:215], v[28:31]
	v_mfma_f32_16x16x32_bf16 v[24:27], v[164:167], v[212:215], v[24:27]
	v_mfma_f32_16x16x32_bf16 v[12:15], v[156:159], v[240:243], v[12:15]
	v_mfma_f32_16x16x32_bf16 v[8:11], v[164:167], v[240:243], v[8:11]
	s_setprio 0
	s_setprio 1
	v_mfma_f32_16x16x32_bf16 v[52:55], v[176:179], v[192:195], v[52:55]
	v_mfma_f32_16x16x32_bf16 v[48:51], v[184:187], v[192:195], v[48:51]
	v_mfma_f32_16x16x32_bf16 v[36:39], v[176:179], v[200:203], v[36:39]
	v_mfma_f32_16x16x32_bf16 v[32:35], v[184:187], v[200:203], v[32:35]
	v_mfma_f32_16x16x32_bf16 v[20:23], v[176:179], v[208:211], v[20:23]
	v_mfma_f32_16x16x32_bf16 v[16:19], v[184:187], v[208:211], v[16:19]
	v_mfma_f32_16x16x32_bf16 v[4:7], v[176:179], v[216:219], v[4:7]
	v_mfma_f32_16x16x32_bf16 v[0:3], v[184:187], v[216:219], v[0:3]
	v_mfma_f32_16x16x32_bf16 v[52:55], v[180:183], v[196:199], v[52:55]
	v_mfma_f32_16x16x32_bf16 v[48:51], v[188:191], v[196:199], v[48:51]
	v_mfma_f32_16x16x32_bf16 v[36:39], v[180:183], v[204:207], v[36:39]
	v_mfma_f32_16x16x32_bf16 v[32:35], v[188:191], v[204:207], v[32:35]
	v_mfma_f32_16x16x32_bf16 v[20:23], v[180:183], v[212:215], v[20:23]
	v_mfma_f32_16x16x32_bf16 v[16:19], v[188:191], v[212:215], v[16:19]
	v_mfma_f32_16x16x32_bf16 v[4:7], v[180:183], v[240:243], v[4:7]
	v_mfma_f32_16x16x32_bf16 v[0:3], v[188:191], v[240:243], v[0:3]
	s_setprio 0
	s_barrier
	s_add_i32 s10, 0, 0x18000
	v_add_u32_e32 v148, s10, v149
	s_add_i32 s62, 0, 0x1c000
	ds_read_b128 v[152:155], v148
	ds_read_b128 v[156:159], v148 offset:1024
	ds_read_b128 v[160:163], v148 offset:2048
	ds_read_b128 v[164:167], v148 offset:3072
	v_add_u32_e32 v148, s62, v149
	ds_read_b128 v[176:179], v148
	ds_read_b128 v[180:183], v148 offset:1024
	ds_read_b128 v[184:187], v148 offset:2048
	ds_read_b128 v[188:191], v148 offset:3072
	v_lshl_add_u64 v[146:147], v[146:147], 0, s[94:95]
	s_mov_b32 m0, s51
	v_lshl_add_u64 v[226:227], v[146:147], 0, v[132:133]
	ds_read_b128 v[192:195], v151 offset:32768
	ds_read_b128 v[196:199], v151 offset:33792
	ds_read_b128 v[200:203], v151 offset:34816
	ds_read_b128 v[204:207], v151 offset:35840
	ds_read_b128 v[208:211], v151 offset:36864
	ds_read_b128 v[212:215], v151 offset:37888
	ds_read_b128 v[216:219], v151 offset:38912
	ds_read_b128 v[240:243], v151 offset:39936
	global_load_lds_dwordx4 v[226:227], off
	v_lshl_add_u64 v[146:147], v[146:147], 0, v[130:131]
	s_mov_b32 m0, s52
	s_nop 0
	global_load_lds_dwordx4 v[146:147], off
	s_waitcnt vmcnt(8)
	s_waitcnt lgkmcnt(0)
	s_barrier
	s_setprio 1
	s_waitcnt lgkmcnt(0)
	v_mfma_f32_16x16x32_bf16 v[124:127], v[152:155], v[192:195], v[124:127]
	v_mfma_f32_16x16x32_bf16 v[120:123], v[160:163], v[192:195], v[120:123]
	v_mfma_f32_16x16x32_bf16 v[108:111], v[152:155], v[200:203], v[108:111]
	v_mfma_f32_16x16x32_bf16 v[104:107], v[160:163], v[200:203], v[104:107]
	v_mfma_f32_16x16x32_bf16 v[92:95], v[152:155], v[208:211], v[92:95]
	v_mfma_f32_16x16x32_bf16 v[88:91], v[160:163], v[208:211], v[88:91]
	v_mfma_f32_16x16x32_bf16 v[76:79], v[152:155], v[216:219], v[76:79]
	v_mfma_f32_16x16x32_bf16 v[72:75], v[160:163], v[216:219], v[72:75]
	v_mfma_f32_16x16x32_bf16 v[124:127], v[156:159], v[196:199], v[124:127]
	v_mfma_f32_16x16x32_bf16 v[120:123], v[164:167], v[196:199], v[120:123]
	v_mfma_f32_16x16x32_bf16 v[108:111], v[156:159], v[204:207], v[108:111]
	v_mfma_f32_16x16x32_bf16 v[104:107], v[164:167], v[204:207], v[104:107]
	v_mfma_f32_16x16x32_bf16 v[92:95], v[156:159], v[212:215], v[92:95]
	v_mfma_f32_16x16x32_bf16 v[88:91], v[164:167], v[212:215], v[88:91]
	v_mfma_f32_16x16x32_bf16 v[76:79], v[156:159], v[240:243], v[76:79]
	v_mfma_f32_16x16x32_bf16 v[72:75], v[164:167], v[240:243], v[72:75]
	s_setprio 0
	s_setprio 1
	v_mfma_f32_16x16x32_bf16 v[116:119], v[176:179], v[192:195], v[116:119]
	v_mfma_f32_16x16x32_bf16 v[112:115], v[184:187], v[192:195], v[112:115]
	v_mfma_f32_16x16x32_bf16 v[100:103], v[176:179], v[200:203], v[100:103]
	v_mfma_f32_16x16x32_bf16 v[96:99], v[184:187], v[200:203], v[96:99]
	v_mfma_f32_16x16x32_bf16 v[84:87], v[176:179], v[208:211], v[84:87]
	v_mfma_f32_16x16x32_bf16 v[80:83], v[184:187], v[208:211], v[80:83]
	v_mfma_f32_16x16x32_bf16 v[68:71], v[176:179], v[216:219], v[68:71]
	v_mfma_f32_16x16x32_bf16 v[64:67], v[184:187], v[216:219], v[64:67]
	v_mfma_f32_16x16x32_bf16 v[116:119], v[180:183], v[196:199], v[116:119]
	v_mfma_f32_16x16x32_bf16 v[112:115], v[188:191], v[196:199], v[112:115]
	v_mfma_f32_16x16x32_bf16 v[100:103], v[180:183], v[204:207], v[100:103]
	v_mfma_f32_16x16x32_bf16 v[96:99], v[188:191], v[204:207], v[96:99]
	v_mfma_f32_16x16x32_bf16 v[84:87], v[180:183], v[212:215], v[84:87]
	v_mfma_f32_16x16x32_bf16 v[80:83], v[188:191], v[212:215], v[80:83]
	v_mfma_f32_16x16x32_bf16 v[68:71], v[180:183], v[240:243], v[68:71]
	v_mfma_f32_16x16x32_bf16 v[64:67], v[188:191], v[240:243], v[64:67]
	s_setprio 0
	s_barrier
; __device__ __forceinline__ unsigned cvt_pk_bf16(float lo, float hi) { unsigned r; asm volatile("v_cvt_pk_bf16_f32 %0, %1, %2" : "=v"(r) : "v"(lo), "v"(hi)); return r; }
; __device__ __forceinline__ float gelu_tanh(float x) { const float u = 0.7978845608028654f * (x + 0.044715f * x * x * x); return x * fast_rcp(1.0f + fast_exp2(-2.0f * LOG2E * u)); }
; #define PG8_MMA(ai, bj, At, Bt) do { __builtin_amdgcn_s_setprio(1); _Pragma("unroll") for (int k = 0; k < 2; ++k) _Pragma("unroll") for (int m = 0; m < 4; ++m) _Pragma("unroll") for (int n = 0; n < 2; ++n) \
;         acc[ai][bj][m][n] = __builtin_amdgcn_mfma_f32_16x16x32_bf16(Bt[n][k], At[m][k], acc[ai][bj][m][n], 0, 0, 0); __builtin_amdgcn_s_setprio(0); } while (0)
; #define PG8_WAIT_V(n) asm volatile("s_waitcnt vmcnt(" #n ")" ::: "memory")
; #define PG8_WAIT_L(n) asm volatile("s_waitcnt lgkmcnt(" #n ")" ::: "memory")
; #define PG8_BAR __builtin_amdgcn_s_barrier()
; #define PG8_SCHED __builtin_amdgcn_sched_barrier(0)
;     __device__ __forceinline__ void operator()(const f32x4 (&acc)[2][2][4][2], const Unit& u, int wr, int wc, int fr, int fq) const {
;         const int row0 = u.pm * BM + wr * 64 + fr, col0 = u.pn * BM + wc * 32 + 8 * fq;
;         float rsv[2][4]; load_rstd(rsv, ssq, row0);
; #pragma unroll
;         for (int ai = 0; ai < 2; ++ai)
; #pragma unroll
;             for (int m = 0; m < 4; ++m) { const int row = row0 + ai * HALF + m * 16; bf16_t* rowp = O + (size_t)row * ldc + col0; const float rs = rsv[ai][m];
; #pragma unroll
;                 for (int bj = 0; bj < 2; ++bj) { f32x4 v0 = acc[ai][bj][m][0] * rs, v1 = acc[ai][bj][m][1] * rs;
;                     if (ACT == 1) {
; #pragma unroll
;                         for (int j = 0; j < 4; ++j) { v0[j] = gelu_tanh(v0[j]); v1[j] = gelu_tanh(v1[j]); } }
;                     u32x4 w; w.x = cvt_pk_bf16(v0[0], v0[1]); w.y = cvt_pk_bf16(v0[2], v0[3]); w.z = cvt_pk_bf16(v1[0], v1[1]); w.w = cvt_pk_bf16(v1[2], v1[3]);
;                     *(u32x4*)(rowp + bj * HALF) = w; } }
; template <class Epi, bool ALIGN_EPI>
; __device__ __forceinline__ void gemm_phase(LAS unsigned char* lds, const Gemm g, const StaticOrder& S, const Epi& E, const int tid) {
;     ...
;             PG8_WAIT_V(8); PG8_WAIT_L(0); PG8_BAR; PG8_MMA(1, 0, At, B0); PG8_MMA(1, 1, At, B1); PG8_BAR; PG8_SCHED;
	s_add_i32 s10, s10, s45
	v_lshl_add_u64 v[146:147], v[244:245], 0, s[92:93]
	s_mov_b32 m0, s10
	ds_read_b128 v[192:195], v151 offset:49152
	ds_read_b128 v[196:199], v151 offset:50176
	ds_read_b128 v[200:203], v151 offset:51200
	ds_read_b128 v[204:207], v151 offset:52224
	ds_read_b128 v[208:211], v151 offset:53248
	ds_read_b128 v[212:215], v151 offset:54272
	ds_read_b128 v[216:219], v151 offset:55296
	ds_read_b128 v[240:243], v151 offset:56320
	global_load_lds_dwordx4 v[146:147], off
	v_lshl_add_u64 v[146:147], v[246:247], 0, s[92:93]
	s_add_i32 m0, s10, 0x2000
	s_add_i32 s10, s62, s45
	global_load_lds_dwordx4 v[146:147], off
	v_lshl_add_u64 v[146:147], v[248:249], 0, s[92:93]
	s_mov_b32 m0, s10
	s_nop 0
	global_load_lds_dwordx4 v[146:147], off
	v_lshl_add_u64 v[146:147], v[220:221], 0, s[92:93]
	s_add_i32 m0, s10, 0x2000
	s_nop 0
	global_load_lds_dwordx4 v[146:147], off
	v_lshl_add_u64 v[146:147], v[250:251], 0, s[92:93]
	s_mov_b32 m0, s53
	s_nop 0
	global_load_lds_dwordx4 v[146:147], off
	v_lshl_add_u64 v[146:147], v[252:253], 0, s[92:93]
	s_mov_b32 m0, s54
	s_nop 0
	global_load_lds_dwordx4 v[146:147], off
	s_waitcnt vmcnt(8)
	s_waitcnt lgkmcnt(0)
	s_barrier
	s_setprio 1
	s_waitcnt lgkmcnt(0)
	v_mfma_f32_16x16x32_bf16 v[60:63], v[152:155], v[192:195], v[60:63]
	v_mfma_f32_16x16x32_bf16 v[56:59], v[160:163], v[192:195], v[56:59]
	v_mfma_f32_16x16x32_bf16 v[44:47], v[152:155], v[200:203], v[44:47]
	v_mfma_f32_16x16x32_bf16 v[40:43], v[160:163], v[200:203], v[40:43]
	v_mfma_f32_16x16x32_bf16 v[28:31], v[152:155], v[208:211], v[28:31]
	v_mfma_f32_16x16x32_bf16 v[24:27], v[160:163], v[208:211], v[24:27]
	v_mfma_f32_16x16x32_bf16 v[12:15], v[152:155], v[216:219], v[12:15]
	v_mfma_f32_16x16x32_bf16 v[8:11], v[160:163], v[216:219], v[8:11]
	v_mfma_f32_16x16x32_bf16 v[60:63], v[156:159], v[196:199], v[60:63]
	v_lshrrev_b32_e32 v171, 8, v170
	v_and_b32_e32 v234, 15, v170
	v_lshl_add_u32 v171, v171, 6, v234
	s_lshl_b32 s98, s61, 8
	v_add_u32_e32 v171, s98, v171
	v_mul_lo_u32 v171, v171, s28
	v_mfma_f32_16x16x32_bf16 v[56:59], v[164:167], v[196:199], v[56:59]
	v_bfe_u32 v234, v170, 6, 2
	v_bfe_u32 v224, v170, 4, 2
	v_lshlrev_b32_e32 v234, 5, v234
	v_lshl_or_b32 v234, v224, 3, v234
	s_lshl_b32 s98, s60, 8
	v_add_u32_e32 v234, s98, v234
	v_mfma_f32_16x16x32_bf16 v[44:47], v[156:159], v[204:207], v[44:47]
	v_add_lshl_u32 v232, v171, v234, 1
	v_mov_b32_e32 v233, 0
	v_lshl_add_u64 v[232:233], v[232:233], 0, s[30:31]
	s_lshl_b32 s98, s28, 5
	s_mov_b32 s99, 0
	v_mul_f32_e32 v124, v172, v124
	v_mfma_f32_16x16x32_bf16 v[40:43], v[164:167], v[204:207], v[40:43]
	v_mul_f32_e32 v125, v172, v125
	v_mul_f32_e32 v126, v172, v126
	v_mul_f32_e32 v127, v172, v127
	v_mul_f32_e32 v120, v172, v120
	v_mul_f32_e32 v121, v172, v121
	v_mul_f32_e32 v122, v172, v122
	v_mfma_f32_16x16x32_bf16 v[28:31], v[156:159], v[212:215], v[28:31]
	v_mul_f32_e32 v123, v172, v123
	v_cvt_pk_bf16_f32 v124, v124, v125
	v_cvt_pk_bf16_f32 v125, v126, v127
	v_cvt_pk_bf16_f32 v126, v120, v121
	v_cvt_pk_bf16_f32 v127, v122, v123
	global_store_dwordx4 v[232:233], v[124:127], off
	v_mfma_f32_16x16x32_bf16 v[24:27], v[164:167], v[212:215], v[24:27]
	v_mul_f32_e32 v116, v172, v116
	v_mul_f32_e32 v117, v172, v117
	v_mul_f32_e32 v118, v172, v118
	v_mul_f32_e32 v119, v172, v119
	v_mul_f32_e32 v112, v172, v112
	v_mul_f32_e32 v113, v172, v113
	v_mfma_f32_16x16x32_bf16 v[12:15], v[156:159], v[240:243], v[12:15]
	v_mul_f32_e32 v114, v172, v114
	v_mul_f32_e32 v115, v172, v115
	v_cvt_pk_bf16_f32 v116, v116, v117
	v_cvt_pk_bf16_f32 v117, v118, v119
	v_cvt_pk_bf16_f32 v118, v112, v113
	v_cvt_pk_bf16_f32 v119, v114, v115
	v_mfma_f32_16x16x32_bf16 v[8:11], v[164:167], v[240:243], v[8:11]
	global_store_dwordx4 v[232:233], v[116:119], off offset:256
	v_lshl_add_u64 v[232:233], v[232:233], 0, s[98:99]
	v_mul_f32_e32 v108, v173, v108
	v_mul_f32_e32 v109, v173, v109
	v_mul_f32_e32 v110, v173, v110
	v_mul_f32_e32 v111, v173, v111
	s_setprio 0
	s_setprio 1
	v_mfma_f32_16x16x32_bf16 v[52:55], v[176:179], v[192:195], v[52:55]
	v_mul_f32_e32 v104, v173, v104
	v_mul_f32_e32 v105, v173, v105
	v_mul_f32_e32 v106, v173, v106
	v_mul_f32_e32 v107, v173, v107
; __device__ __forceinline__ unsigned cvt_pk_bf16(float lo, float hi) { unsigned r; asm volatile("v_cvt_pk_bf16_f32 %0, %1, %2" : "=v"(r) : "v"(lo), "v"(hi)); return r; }
; __device__ __forceinline__ float gelu_tanh(float x) { const float u = 0.7978845608028654f * (x + 0.044715f * x * x * x); return x * fast_rcp(1.0f + fast_exp2(-2.0f * LOG2E * u)); }
; #define PG8_BAR __builtin_amdgcn_s_barrier()
;     __device__ __forceinline__ void operator()(const f32x4 (&acc)[2][2][4][2], const Unit& u, int wr, int wc, int fr, int fq) const {
;     ...
;             for (int m = 0; m < 4; ++m) { const int row = row0 + ai * HALF + m * 16; bf16_t* rowp = O + (size_t)row * ldc + col0; const float rs = rsv[ai][m];
; #pragma unroll
;                 for (int bj = 0; bj < 2; ++bj) { f32x4 v0 = acc[ai][bj][m][0] * rs, v1 = acc[ai][bj][m][1] * rs;
;                     if (ACT == 1) {
; #pragma unroll
;                         for (int j = 0; j < 4; ++j) { v0[j] = gelu_tanh(v0[j]); v1[j] = gelu_tanh(v1[j]); } }
;                     u32x4 w; w.x = cvt_pk_bf16(v0[0], v0[1]); w.y = cvt_pk_bf16(v0[2], v0[3]); w.z = cvt_pk_bf16(v1[0], v1[1]); w.w = cvt_pk_bf16(v1[2], v1[3]);
;                     *(u32x4*)(rowp + bj * HALF) = w; } }
; template <class Epi, bool ALIGN_EPI>
; __device__ __forceinline__ void gemm_phase(LAS unsigned char* lds, const Gemm g, const StaticOrder& S, const Epi& E, const int tid) {
;     ...
;         if constexpr (ALIGN_EPI) { if (wr == 0) PG8_BAR; }
;         { int t2 = tid; asm volatile("" : "+v"(t2)); const int l2 = t2 & 63, w2 = __builtin_amdgcn_readfirstlane(t2 >> 6); E(acc, cur, w2 >> 2, w2 & 3, l2 & 15, l2 >> 4); }
;         if (!has_next) break;
; #pragma unroll
;         for (int a = 0; a < 2; ++a)
; #pragma unroll
;             for (int b = 0; b < 2; ++b)
; #pragma unroll
;                 for (int m = 0; m < 4; ++m)
; #pragma unroll
;                     for (int n = 0; n < 2; ++n) acc[a][b][m][n] = (f32x4){0.f, 0.f, 0.f, 0.f};
;         cur = nxt; cA = nA; cB = nB; ++ui;
	v_cvt_pk_bf16_f32 v108, v108, v109
	v_cvt_pk_bf16_f32 v109, v110, v111
	v_mfma_f32_16x16x32_bf16 v[48:51], v[184:187], v[192:195], v[48:51]
	v_cvt_pk_bf16_f32 v110, v104, v105
	v_cvt_pk_bf16_f32 v111, v106, v107
	global_store_dwordx4 v[232:233], v[108:111], off
	v_mul_f32_e32 v100, v173, v100
	v_mul_f32_e32 v101, v173, v101
	v_mul_f32_e32 v102, v173, v102
	v_mfma_f32_16x16x32_bf16 v[36:39], v[176:179], v[200:203], v[36:39]
	v_mul_f32_e32 v103, v173, v103
	v_mul_f32_e32 v96, v173, v96
	v_mul_f32_e32 v97, v173, v97
	v_mul_f32_e32 v98, v173, v98
	v_mul_f32_e32 v99, v173, v99
	v_cvt_pk_bf16_f32 v100, v100, v101
	v_mfma_f32_16x16x32_bf16 v[32:35], v[184:187], v[200:203], v[32:35]
	v_cvt_pk_bf16_f32 v101, v102, v103
	v_cvt_pk_bf16_f32 v102, v96, v97
	v_cvt_pk_bf16_f32 v103, v98, v99
	global_store_dwordx4 v[232:233], v[100:103], off offset:256
	v_lshl_add_u64 v[232:233], v[232:233], 0, s[98:99]
	v_mul_f32_e32 v92, v236, v92
	v_mfma_f32_16x16x32_bf16 v[20:23], v[176:179], v[208:211], v[20:23]
	v_mul_f32_e32 v93, v236, v93
	v_mul_f32_e32 v94, v236, v94
	v_mul_f32_e32 v95, v236, v95
	v_mul_f32_e32 v88, v236, v88
	v_mul_f32_e32 v89, v236, v89
	v_mul_f32_e32 v90, v236, v90
	v_mfma_f32_16x16x32_bf16 v[16:19], v[184:187], v[208:211], v[16:19]
	v_mul_f32_e32 v91, v236, v91
	v_cvt_pk_bf16_f32 v92, v92, v93
	v_cvt_pk_bf16_f32 v93, v94, v95
	v_cvt_pk_bf16_f32 v94, v88, v89
	v_cvt_pk_bf16_f32 v95, v90, v91
	global_store_dwordx4 v[232:233], v[92:95], off
	v_mfma_f32_16x16x32_bf16 v[4:7], v[176:179], v[216:219], v[4:7]
	v_mul_f32_e32 v84, v236, v84
	v_mul_f32_e32 v85, v236, v85
	v_mul_f32_e32 v86, v236, v86
	v_mul_f32_e32 v87, v236, v87
	v_mul_f32_e32 v80, v236, v80
	v_mul_f32_e32 v81, v236, v81
	v_mfma_f32_16x16x32_bf16 v[0:3], v[184:187], v[216:219], v[0:3]
	v_mul_f32_e32 v82, v236, v82
	v_mul_f32_e32 v83, v236, v83
	v_cvt_pk_bf16_f32 v84, v84, v85
	v_cvt_pk_bf16_f32 v85, v86, v87
	v_cvt_pk_bf16_f32 v86, v80, v81
	v_cvt_pk_bf16_f32 v87, v82, v83
	v_mfma_f32_16x16x32_bf16 v[52:55], v[180:183], v[196:199], v[52:55]
	global_store_dwordx4 v[232:233], v[84:87], off offset:256
	v_lshl_add_u64 v[232:233], v[232:233], 0, s[98:99]
	v_mul_f32_e32 v76, v237, v76
	v_mul_f32_e32 v77, v237, v77
	v_mul_f32_e32 v78, v237, v78
	v_mul_f32_e32 v79, v237, v79
	v_mfma_f32_16x16x32_bf16 v[48:51], v[188:191], v[196:199], v[48:51]
	v_mul_f32_e32 v72, v237, v72
	v_mul_f32_e32 v73, v237, v73
	v_mul_f32_e32 v74, v237, v74
	v_mul_f32_e32 v75, v237, v75
	v_cvt_pk_bf16_f32 v76, v76, v77
	v_cvt_pk_bf16_f32 v77, v78, v79
	v_mfma_f32_16x16x32_bf16 v[36:39], v[180:183], v[204:207], v[36:39]
	v_cvt_pk_bf16_f32 v78, v72, v73
	v_cvt_pk_bf16_f32 v79, v74, v75
	global_store_dwordx4 v[232:233], v[76:79], off
	v_mul_f32_e32 v68, v237, v68
	v_mul_f32_e32 v69, v237, v69
	v_mul_f32_e32 v70, v237, v70
	v_mfma_f32_16x16x32_bf16 v[32:35], v[188:191], v[204:207], v[32:35]
	v_mul_f32_e32 v71, v237, v71
	v_mul_f32_e32 v64, v237, v64
	v_mul_f32_e32 v65, v237, v65
	v_mul_f32_e32 v66, v237, v66
	v_mul_f32_e32 v67, v237, v67
	v_cvt_pk_bf16_f32 v68, v68, v69
	v_mfma_f32_16x16x32_bf16 v[20:23], v[180:183], v[212:215], v[20:23]
	v_cvt_pk_bf16_f32 v69, v70, v71
	v_cvt_pk_bf16_f32 v70, v64, v65
	v_cvt_pk_bf16_f32 v71, v66, v67
	global_store_dwordx4 v[232:233], v[68:71], off offset:256
	v_lshl_add_u64 v[232:233], v[232:233], 0, s[98:99]
	v_lshl_add_u64 v[232:233], v[232:233], 0, s[98:99]
	v_mfma_f32_16x16x32_bf16 v[16:19], v[188:191], v[212:215], v[16:19]
	v_lshl_add_u64 v[232:233], v[232:233], 0, s[98:99]
	v_lshl_add_u64 v[232:233], v[232:233], 0, s[98:99]
	v_lshl_add_u64 v[232:233], v[232:233], 0, s[98:99]
	v_mfma_f32_16x16x32_bf16 v[4:7], v[180:183], v[240:243], v[4:7]
	v_mfma_f32_16x16x32_bf16 v[0:3], v[188:191], v[240:243], v[0:3]
	s_setprio 0
	s_barrier
	v_lshl_add_u64 v[142:143], v[142:143], 0, s[80:81]
	v_lshl_add_u64 v[144:145], v[144:145], 0, s[80:81]
	s_and_b64 vcc, exec, s[8:9]
	s_cbranch_vccnz .Lq5_notdefer
	s_cmp_lg_u32 s59, s61
	s_cbranch_scc1 .Lq5_notdefer
	s_mov_b32 s101, 1
	s_mov_b32 s60, s58
	s_mov_b32 s61, s59
	v_mov_b64_e32 v[144:145], v[140:141]
	v_mov_b64_e32 v[142:143], v[138:139]
	s_branch .LBB0_346
